# attention unit rewritten in 16x16x32 MFMA layout (own Q frags, masked diagonal tiles, LDS-based differential combine + sub-LN), conflict-free K swizzle
# baseline (speedup 1.0000x reference)
.LBB0_398:
	s_or_b64 exec, exec, s[10:11]
	s_mov_b64 s[10:11], s[84:85]
	s_waitcnt lgkmcnt(0)
	v_mov_b32_e32 v0, v173
	s_barrier
	s_getreg_b32 s1, hwreg(HW_REG_HW_ID, 0, 7)
	s_and_b32 s1, s1, 63
	s_lshl_b32 s1, s1, 2
	v_mov_b32_e32 v1, s1
	ds_read_b32 v6, v1
	s_load_dwordx8 s[12:19], s[10:11], 0x90
	v_and_b32_e32 v1, 63, v0
	s_lshl_b32 s66, s70, 6
	v_or_b32_e32 v160, s66, v1
	v_lshlrev_b64 v[2:3], 2, v[160:161]
	s_waitcnt lgkmcnt(0)
	v_lshl_add_u64 v[4:5], s[12:13], 0, v[2:3]
	global_load_dword v7, v[4:5], off
	v_lshl_add_u64 v[4:5], s[14:15], 0, v[2:3]
	global_load_dword v8, v[4:5], off
	v_lshl_add_u64 v[4:5], s[16:17], 0, v[2:3]
	v_lshl_add_u64 v[2:3], s[18:19], 0, v[2:3]
	global_load_dword v4, v[4:5], off
	v_readfirstlane_b32 s1, v6
	global_load_dword v2, v[2:3], off
	s_load_dwordx2 s[12:13], s[10:11], 0xb0
	s_getreg_b32 s6, hwreg(HW_REG_HW_ID, 0, 7)
	s_and_b32 s6, s6, 63
	s_lshl_b32 s6, s6, 2
	s_lshl_b32 s1, s1, 6
	s_and_b32 s1, s1, 0x3fc0
	s_waitcnt vmcnt(2)
	v_mul_f32_e32 v3, v7, v8
	ds_bpermute_b32 v3, v176, v3
	s_waitcnt vmcnt(0)
	v_mul_f32_e32 v5, v4, v2
	ds_bpermute_b32 v5, v176, v5
	s_waitcnt lgkmcnt(0)
	v_fmac_f32_e32 v3, v7, v8
	v_mov_b32_e32 v7, s6
	v_readlane_b32 s6, v255, 12
	v_readlane_b32 s7, v255, 13
	v_fmac_f32_e32 v5, v4, v2
	ds_bpermute_b32 v2, v177, v3
	ds_bpermute_b32 v4, v177, v5
	s_and_b64 vcc, exec, s[6:7]
	s_waitcnt lgkmcnt(1)
	v_add_f32_e32 v2, v3, v2
	s_waitcnt lgkmcnt(0)
	v_add_f32_e32 v3, v5, v4
	ds_bpermute_b32 v4, v178, v2
	ds_bpermute_b32 v5, v178, v3
	s_waitcnt lgkmcnt(1)
	v_add_f32_e32 v2, v2, v4
	s_waitcnt lgkmcnt(0)
	v_add_f32_e32 v3, v3, v5
	ds_bpermute_b32 v4, v179, v2
	ds_bpermute_b32 v5, v179, v3
	s_waitcnt lgkmcnt(1)
	v_add_f32_e32 v2, v2, v4
	s_waitcnt lgkmcnt(0)
	v_add_f32_e32 v3, v3, v5
	ds_bpermute_b32 v4, v180, v2
	ds_bpermute_b32 v6, v180, v3
	s_waitcnt lgkmcnt(1)
	v_add_f32_e32 v5, v2, v4
	s_waitcnt lgkmcnt(0)
	v_add_f32_e32 v3, v3, v6
	ds_bpermute_b32 v6, v181, v5
	ds_bpermute_b32 v4, v181, v3
	ds_read_b32 v2, v7
	s_waitcnt lgkmcnt(0)
	v_add_u32_e32 v2, s1, v0
	s_nop 0
	v_readfirstlane_b32 s1, v2
	s_cbranch_vccnz .LBB0_423
	v_cvt_f32_u32_e32 v7, s70
	s_mov_b32 s8, 0x3fb8aa3b
	s_load_dwordx2 s[42:43], s[10:11], 0xe0
	v_add_f32_e32 v5, v5, v6
	v_mul_f32_e32 v7, 0xbe99999a, v7
	v_mul_f32_e32 v8, 0x3fb8aa3b, v7
	v_fma_f32 v9, v7, s8, -v8
	v_rndne_f32_e32 v10, v8
	v_fmac_f32_e32 v9, 0x32a5705f, v7
	v_sub_f32_e32 v8, v8, v10
	v_add_f32_e32 v8, v8, v9
	v_exp_f32_e32 v8, v8
	v_cvt_i32_f32_e32 v9, v10
	s_waitcnt lgkmcnt(0)
	s_add_u32 s48, s42, 0xc000000
	s_addc_u32 s49, s43, 0
	v_mul_f32_e32 v6, 0x3fb8aa3b, v5
	s_add_u32 s59, s42, 0x3000000
	v_ldexp_f32 v8, v8, v9
	v_fma_f32 v9, v5, s8, -v6
	v_rndne_f32_e32 v10, v6
	s_addc_u32 s67, s43, 0
	s_lshl_b32 s40, s70, 7
	v_fmac_f32_e32 v9, 0x32a5705f, v5
	v_sub_f32_e32 v6, v6, v10
	s_lshl_b64 s[6:7], s[40:41], 2
	v_add_f32_e32 v6, v6, v9
	s_add_u32 s56, s12, s6
	s_mov_b32 s6, 0xc2ce8ed0
	v_exp_f32_e32 v6, v6
	v_cvt_i32_f32_e32 v9, v10
	s_addc_u32 s57, s13, s7
	v_cmp_ngt_f32_e32 vcc, s6, v7
	s_mov_b32 s7, 0x42b17218
	v_add_f32_e32 v3, v3, v4
	v_cndmask_b32_e32 v8, 0, v8, vcc
	v_cmp_nlt_f32_e32 vcc, s7, v7
	v_mul_f32_e32 v4, 0x3fb8aa3b, v3
	v_ldexp_f32 v6, v6, v9
	v_cndmask_b32_e32 v7, v196, v8, vcc
	v_mov_b32_e32 v8, 0x3f4ccccd
	v_fmamk_f32 v7, v7, 0xbf19999a, v8
	v_fma_f32 v8, v3, s8, -v4
	v_rndne_f32_e32 v9, v4
	v_fmac_f32_e32 v8, 0x32a5705f, v3
	v_sub_f32_e32 v4, v4, v9
	v_add_f32_e32 v4, v4, v8
	v_exp_f32_e32 v4, v4
	v_cvt_i32_f32_e32 v8, v9
	v_cmp_ngt_f32_e32 vcc, s6, v5
	v_writelane_b32 v255, s70, 16
	v_and_b32_e32 v199, 31, v0
	v_cndmask_b32_e32 v6, 0, v6, vcc
	v_cmp_nlt_f32_e32 vcc, s7, v5
	v_ldexp_f32 v4, v4, v8
	v_bfe_u32 v8, v0, 1, 3
	v_cndmask_b32_e32 v5, v196, v6, vcc
	v_cmp_ngt_f32_e32 vcc, s6, v3
	s_ashr_i32 s6, s1, 6
	s_ashr_i32 s1, s1, 8
	v_cndmask_b32_e32 v4, 0, v4, vcc
	v_cmp_nlt_f32_e32 vcc, s7, v3
	s_lshl_b32 s7, s6, 5
	s_and_b32 s68, s7, 0x60
	v_cndmask_b32_e32 v3, v196, v4, vcc
	s_lshl_b32 s69, s1, 6
	v_sub_f32_e32 v3, v5, v3
	s_add_u32 s70, s42, 0xc000400
	v_add_f32_e32 v170, v7, v3
	v_lshrrev_b32_e32 v3, 5, v1
	s_addc_u32 s71, s43, 0
	s_lshl_b32 s10, s1, 13
	v_lshrrev_b32_e32 v6, 1, v0
	s_cmp_eq_u32 s1, 1
	v_bitop3_b32 v6, v3, v6, 7 bitop3:0x78
	s_cselect_b64 s[60:61], -1, 0
	s_cmp_lt_u32 s6, 4
	v_lshlrev_b32_e32 v201, 4, v6
	v_bitop3_b32 v6, v3, v8, 2 bitop3:0x36
	v_lshrrev_b32_e32 v1, 3, v1
	v_lshlrev_b32_e32 v4, 3, v3
	v_lshlrev_b32_e32 v5, 7, v199
	v_lshlrev_b32_e32 v172, 2, v3
	v_lshlrev_b32_e32 v10, 4, v3
	s_cselect_b64 s[62:63], -1, 0
	v_lshlrev_b32_e32 v202, 4, v6
	v_bitop3_b32 v6, v3, v8, 4 bitop3:0x36
	v_bitop3_b32 v3, v3, v8, 6 bitop3:0x36
	v_lshl_or_b32 v1, s6, 3, v1
	s_movk_i32 s1, 0x600
	s_add_i32 s12, s10, 0x120
	v_lshlrev_b32_e32 v203, 4, v6
	v_lshlrev_b32_e32 v204, 4, v3
	v_lshrrev_b32_e32 v3, 1, v1
	v_mul_lo_u32 v6, v1, s1
	s_lshl_b32 s1, s6, 10
	s_add_i32 s11, s44, 0x120
	v_add_u32_e32 v207, s12, v5
	s_add_i32 s12, s46, 0x120
	v_xor_b32_e32 v3, v3, v0
	s_add_i32 s72, s1, 0x120
	s_add_i32 s52, s11, s1
	s_add_i32 s92, s12, s1
	s_add_i32 s1, s45, 0x120
	v_lshlrev_b32_e32 v3, 3, v3
	v_add_u32_e32 v211, s1, v5
	s_add_i32 s1, s47, 0x120
	v_lshlrev_b32_e32 v0, 5, v0
	v_or_b32_e32 v9, s68, v199
	v_and_b32_e32 v3, 56, v3
	v_lshlrev_b32_e32 v1, 15, v1
	v_add_u32_e32 v212, s1, v5
	s_movk_i32 s1, 0x210
	v_ashrrev_i32_e32 v213, 2, v2
	v_and_b32_e32 v0, 0x60, v0
	v_or_b32_e32 v6, v3, v6
	v_lshl_or_b32 v206, v3, 1, v1
	s_add_i32 s11, s11, s10
	s_add_i32 s12, s12, s10
	v_mad_u32_u24 v1, v9, s1, v195
	v_mul_lo_u32 v2, v213, s1
	v_lshlrev_b32_e32 v3, 2, v0
	s_movk_i32 s1, 0x120
	v_sub_f32_e32 v200, 1.0, v7
	v_lshlrev_b32_e32 v205, 1, v6
	s_lshr_b32 s14, s68, 5
	s_lshr_b32 s15, s69, 4
	s_or_b32 s14, s14, s15
	v_lshrrev_b32_e32 v216, 3, v173
	v_lshl_or_b32 v216, s14, 3, v216
	v_bfe_u32 v217, v216, 1, 1
	v_bfe_u32 v218, v216, 2, 1
	v_bfe_u32 v219, v216, 4, 1
	v_xor_b32_e32 v218, v218, v219
	v_lshl_or_b32 v217, v219, 1, v217
	v_lshl_or_b32 v217, v218, 2, v217
	v_and_b32_e32 v218, 7, v173
	v_xor_b32_e32 v217, v218, v217
	v_mul_u32_u24_e32 v216, 0xc00, v216
	v_lshl_add_u32 v205, v217, 4, v216
	s_add_i32 s73, s72, 0x2000
	s_add_i32 s6, s72, 0x4000
	s_add_i32 s7, s72, 0x6000
	s_add_i32 s8, s72, 0x8000
	s_add_i32 s9, s72, 0xa000
	s_add_i32 s58, s72, 0xc000
	s_add_i32 s79, s72, 0xe000
	s_add_i32 s53, s52, 0x2000
	s_add_i32 s90, s52, 0x4000
	s_add_i32 s91, s52, 0x6000
	s_add_i32 s93, s92, 0x2000
	s_add_i32 s94, s92, 0x4000
	s_add_i32 s95, s92, 0x6000
	v_add_u32_e32 v208, 0x120, v5
	v_add_u32_e32 v209, s11, v5
	v_add_u32_e32 v210, s12, v5
	v_add3_u32 v214, s1, v2, v3
	v_mov_b32_e32 v171, v170
	v_lshlrev_b32_e32 v174, 1, v4
	v_lshlrev_b32_e32 v160, 1, v0
	v_add_u32_e32 v215, v1, v10
	s_mov_b32 s96, s2
	s_branch .LBB0_401

.LBB0_404:
	v_readfirstlane_b32 s13, v0
	s_nop 1
	v_cmp_eq_u32_e32 vcc, s13, v0
	s_and_saveexec_b64 vcc, vcc
	s_nop 0
	buffer_load_dwordx4 v205, s[28:31], s13 offen lds
	s_xor_b64 exec, exec, vcc
	s_cbranch_execnz .LBB0_404
	s_mov_b64 exec, s[10:11]
	s_mov_b32 m0, s90
	v_add_u32_e32 v175, v207, v201
	buffer_load_dwordx4 v206, s[36:39], s12 offen lds
	s_bitset1_b32 s12, 21
	s_mov_b32 m0, s91
	v_add_u32_e32 v217, v207, v202
	buffer_load_dwordx4 v206, s[36:39], s12 offen lds
	s_waitcnt vmcnt(4)
	s_barrier
	ds_read_b128 v[0:3], v175 offset:4096
	ds_read_b128 v[4:7], v175
	s_waitcnt vmcnt(15) lgkmcnt(0)
	v_mfma_f32_32x32x16_bf16 v[112:127], v[4:7], v[140:143], 0
	v_add_u32_e32 v218, v207, v203
	v_add_u32_e32 v219, v207, v204
	s_or_b32 s10, s85, 1
	s_mov_b32 s12, 0
	s_cmp_lt_u32 s1, 2
	v_mfma_f32_32x32x16_bf16 v[96:111], v[0:3], v[140:143], 0
	ds_read_b128 v[0:3], v217 offset:4096
	ds_read_b128 v[4:7], v217
	s_waitcnt vmcnt(14) lgkmcnt(0)
	v_mfma_f32_32x32x16_bf16 v[112:127], v[4:7], v[136:139], v[112:127]
	v_mfma_f32_32x32x16_bf16 v[96:111], v[0:3], v[136:139], v[96:111]
	ds_read_b128 v[0:3], v218 offset:4096
	ds_read_b128 v[4:7], v218
	s_waitcnt vmcnt(13) lgkmcnt(0)
	v_mfma_f32_32x32x16_bf16 v[112:127], v[4:7], v[132:135], v[112:127]
	v_mfma_f32_32x32x16_bf16 v[96:111], v[0:3], v[132:135], v[96:111]
	ds_read_b128 v[0:3], v219 offset:4096
	ds_read_b128 v[4:7], v219
	s_waitcnt vmcnt(12) lgkmcnt(0)
	v_mfma_f32_32x32x16_bf16 v[112:127], v[4:7], v[128:131], v[112:127]
	v_mfma_f32_32x32x16_bf16 v[96:111], v[0:3], v[128:131], v[96:111]
	s_mov_b32 s14, 0
	s_mov_b32 s15, s10
	s_mov_b32 s16, s85
	s_mov_b32 s38, s30
	s_mov_b32 s39, s31
	v_and_b32_e32 v250, 15, v173
	v_lshrrev_b32_e32 v251, 4, v173
	v_add_u32_e32 v252, s84, v250
	v_mul_u32_u24_e32 v252, 0xc00, v252
	v_lshl_add_u32 v252, v251, 4, v252
	s_add_i32 s17, s97, s69
	s_lshl_b32 s17, s17, 1
	v_add_u32_e32 v222, s17, v252
	v_mov_b32_e32 v223, 0
	v_lshl_add_u64 v[222:223], s[48:49], 0, v[222:223]
	global_load_dwordx4 v[128:131], v[222:223], off
	global_load_dwordx4 v[132:135], v[222:223], off offset:64
	s_mov_b64 s[18:19], 0xc000
	v_lshl_add_u64 v[222:223], v[222:223], 0, s[18:19]
	global_load_dwordx4 v[136:139], v[222:223], off
	global_load_dwordx4 v[140:143], v[222:223], off offset:64
	v_and_b32_e32 v252, 7, v250
	v_lshrrev_b32_e32 v253, 3, v250
	v_lshl_add_u32 v222, v253, 4, v252
	v_bfe_u32 v223, v250, 1, 1
	v_lshl_or_b32 v223, v253, 1, v223
	v_xor_b32_e32 v223, v223, v251
	v_lshlrev_b32_e32 v223, 4, v223
	v_lshl_add_u32 v240, v222, 7, v223
	v_bfe_u32 v222, v250, 2, 1
	v_xor_b32_e32 v222, v222, v253
	v_lshl_add_u32 v240, v222, 6, v240
	s_lshl_b32 s17, s69, 7
	s_add_i32 s17, s17, 0x120
	v_add_u32_e32 v240, s17, v240
	v_lshlrev_b32_e32 v222, 7, v222
	v_sub_u32_e32 v241, v240, v222
	v_add_u32_e32 v241, 64, v241
	v_add_u32_e32 v217, 0x10000, v240
	v_add_u32_e32 v218, 0x10000, v241
	v_bfe_u32 v222, v250, 1, 2
	v_xor_b32_e32 v222, v222, v251
	v_lshlrev_b32_e32 v222, 4, v222
	v_lshl_add_u32 v222, v250, 7, v222
	v_lshl_add_u32 v242, v253, 6, v222
	v_add_u32_e32 v242, 0x4120, v242
	v_lshlrev_b32_e32 v223, 7, v253
	v_sub_u32_e32 v243, v242, v223
	v_add_u32_e32 v243, 64, v243
	v_add_u32_e32 v244, 0x10000, v242
	v_add_u32_e32 v245, 0x10000, v243
	v_and_b32_e32 v222, 1, v251
	v_lshrrev_b32_e32 v223, 1, v251
	v_lshlrev_b32_e32 v222, 2, v222
	v_lshl_add_u32 v222, v223, 4, v222
	v_add_u32_e32 v246, s84, v250
	v_sub_u32_e32 v246, v246, v222
	v_add_u32_e32 v247, 16, v246
	v_mov_b32_e32 v220, 0
	v_mov_b32_e32 v221, 0
	v_mov_b32_e32 v0, 0
	v_mov_b32_e32 v1, 0
	v_mov_b32_e32 v2, 0
	v_mov_b32_e32 v3, 0
	v_mov_b32_e32 v4, 0
	v_mov_b32_e32 v5, 0
	v_mov_b32_e32 v6, 0
	v_mov_b32_e32 v7, 0
	v_mov_b32_e32 v8, 0
	v_mov_b32_e32 v9, 0
	v_mov_b32_e32 v10, 0
	v_mov_b32_e32 v11, 0
	v_mov_b32_e32 v12, 0
	v_mov_b32_e32 v13, 0
	v_mov_b32_e32 v14, 0
	v_mov_b32_e32 v15, 0
	v_mov_b32_e32 v16, 0
	v_mov_b32_e32 v17, 0
	v_mov_b32_e32 v18, 0
	v_mov_b32_e32 v19, 0
	v_mov_b32_e32 v20, 0
	v_mov_b32_e32 v21, 0
	v_mov_b32_e32 v22, 0
	v_mov_b32_e32 v23, 0
	v_mov_b32_e32 v24, 0
	v_mov_b32_e32 v25, 0
	v_mov_b32_e32 v26, 0
	v_mov_b32_e32 v27, 0
	v_mov_b32_e32 v28, 0
	v_mov_b32_e32 v29, 0
	v_mov_b32_e32 v30, 0
	v_mov_b32_e32 v31, 0
	v_mov_b32_e32 v32, 0
	v_mov_b32_e32 v33, 0
	v_mov_b32_e32 v34, 0
	v_mov_b32_e32 v35, 0
	v_mov_b32_e32 v36, 0
	v_mov_b32_e32 v37, 0
	v_mov_b32_e32 v38, 0
	v_mov_b32_e32 v39, 0
	v_mov_b32_e32 v40, 0
	v_mov_b32_e32 v41, 0
	v_mov_b32_e32 v42, 0
	v_mov_b32_e32 v43, 0
	v_mov_b32_e32 v44, 0
	v_mov_b32_e32 v45, 0
	v_mov_b32_e32 v46, 0
	v_mov_b32_e32 v47, 0
	v_mov_b32_e32 v48, 0
	v_mov_b32_e32 v49, 0
	v_mov_b32_e32 v50, 0
	v_mov_b32_e32 v51, 0
	v_mov_b32_e32 v52, 0
	v_mov_b32_e32 v53, 0
	v_mov_b32_e32 v54, 0
	v_mov_b32_e32 v55, 0
	v_mov_b32_e32 v56, 0
	v_mov_b32_e32 v57, 0
	v_mov_b32_e32 v58, 0
	v_mov_b32_e32 v59, 0
	v_mov_b32_e32 v60, 0
	v_mov_b32_e32 v61, 0
	v_mov_b32_e32 v62, 0
	v_mov_b32_e32 v63, 0
	ds_read_b128 v[144:147], v240
	ds_read_b128 v[148:151], v240 offset:1024
	ds_read_b128 v[152:155], v240 offset:4096
	ds_read_b128 v[156:159], v240 offset:5120
	ds_read_b128 v[224:227], v241
	ds_read_b128 v[228:231], v241 offset:1024
	ds_read_b128 v[232:235], v241 offset:4096
	ds_read_b128 v[236:239], v241 offset:5120
	s_waitcnt vmcnt(0) lgkmcnt(0)
	v_mfma_f32_16x16x32_bf16 v[96:99], v[144:147], v[128:131], 0
	v_mfma_f32_16x16x32_bf16 v[104:107], v[144:147], v[136:139], 0
	v_mfma_f32_16x16x32_bf16 v[100:103], v[148:151], v[128:131], 0
	v_mfma_f32_16x16x32_bf16 v[108:111], v[148:151], v[136:139], 0
	v_mfma_f32_16x16x32_bf16 v[112:115], v[152:155], v[128:131], 0
	v_mfma_f32_16x16x32_bf16 v[120:123], v[152:155], v[136:139], 0
	v_mfma_f32_16x16x32_bf16 v[116:119], v[156:159], v[128:131], 0
	v_mfma_f32_16x16x32_bf16 v[124:127], v[156:159], v[136:139], 0
	v_mfma_f32_16x16x32_bf16 v[96:99], v[224:227], v[132:135], v[96:99]
	v_mfma_f32_16x16x32_bf16 v[104:107], v[224:227], v[140:143], v[104:107]
	v_mfma_f32_16x16x32_bf16 v[100:103], v[228:231], v[132:135], v[100:103]
	v_mfma_f32_16x16x32_bf16 v[108:111], v[228:231], v[140:143], v[108:111]
	v_mfma_f32_16x16x32_bf16 v[112:115], v[232:235], v[132:135], v[112:115]
	v_mfma_f32_16x16x32_bf16 v[120:123], v[232:235], v[140:143], v[120:123]
	v_mfma_f32_16x16x32_bf16 v[116:119], v[236:239], v[132:135], v[116:119]
	v_mfma_f32_16x16x32_bf16 v[124:127], v[236:239], v[140:143], v[124:127]
	ds_read_b128 v[144:147], v240 offset:32768
	ds_read_b128 v[148:151], v240 offset:33792
	ds_read_b128 v[152:155], v240 offset:36864
	ds_read_b128 v[156:159], v240 offset:37888
	s_cmp_lt_u32 s16, 4
	s_cbranch_scc1 .La16_rem_check
.La16_main:
	s_add_i32 s17, s14, 3
	s_min_u32 s17, s17, s15
	s_mul_i32 s18, s17, 0x30000
	s_lshl_b32 s19, s17, 7
	s_or_b32 s12, s18, 0x80
	s_add_i32 s13, s19, 0x200000
	ds_read_b128 v[224:227], v241 offset:32768
	ds_read_b128 v[228:231], v241 offset:33792
	ds_read_b128 v[232:235], v241 offset:36864
	ds_read_b128 v[236:239], v241 offset:37888
	s_waitcnt lgkmcnt(4)
	v_mfma_f32_16x16x32_bf16 v[64:67], v[144:147], v[128:131], 0
	v_exp_f32_e32 v96, v96
	v_exp_f32_e32 v97, v97
	v_add_f32_e32 v220, v220, v96
	v_add_f32_e32 v220, v220, v97
	v_mfma_f32_16x16x32_bf16 v[72:75], v[144:147], v[136:139], 0
	v_exp_f32_e32 v98, v98
	v_exp_f32_e32 v99, v99
	v_add_f32_e32 v220, v220, v98
	v_add_f32_e32 v220, v220, v99
	v_mfma_f32_16x16x32_bf16 v[68:71], v[148:151], v[128:131], 0
	v_exp_f32_e32 v100, v100
	v_exp_f32_e32 v101, v101
	v_cvt_pk_bf16_f32 v96, v96, v97
	v_add_f32_e32 v220, v220, v100
	v_mfma_f32_16x16x32_bf16 v[76:79], v[148:151], v[136:139], 0
	v_exp_f32_e32 v102, v102
	v_cvt_pk_bf16_f32 v97, v98, v99
	v_add_f32_e32 v220, v220, v101
	v_mfma_f32_16x16x32_bf16 v[80:83], v[152:155], v[128:131], 0
	v_exp_f32_e32 v103, v103
	v_cvt_pk_bf16_f32 v98, v100, v101
	v_cvt_pk_bf16_f32 v99, v102, v103
	v_mfma_f32_16x16x32_bf16 v[88:91], v[152:155], v[136:139], 0
	v_exp_f32_e32 v104, v104
	v_add_f32_e32 v220, v220, v102
	v_add_f32_e32 v221, v221, v104
	v_mfma_f32_16x16x32_bf16 v[84:87], v[156:159], v[128:131], 0
	v_exp_f32_e32 v105, v105
	v_add_f32_e32 v220, v220, v103
	v_add_f32_e32 v221, v221, v105
	v_mfma_f32_16x16x32_bf16 v[92:95], v[156:159], v[136:139], 0
	v_exp_f32_e32 v106, v106
	v_cvt_pk_bf16_f32 v104, v104, v105
	v_add_f32_e32 v221, v221, v106
	ds_read_b128 v[144:147], v242
	ds_read_b128 v[148:151], v242 offset:2048
	ds_read_b128 v[152:155], v242 offset:4096
	ds_read_b128 v[156:159], v242 offset:6144
	s_waitcnt lgkmcnt(4)
	v_mfma_f32_16x16x32_bf16 v[64:67], v[224:227], v[132:135], v[64:67]
	v_exp_f32_e32 v107, v107
	v_mfma_f32_16x16x32_bf16 v[72:75], v[224:227], v[140:143], v[72:75]
	v_exp_f32_e32 v108, v108
	v_add_f32_e32 v221, v221, v107
	v_cvt_pk_bf16_f32 v105, v106, v107
	v_mfma_f32_16x16x32_bf16 v[68:71], v[228:231], v[132:135], v[68:71]
	v_exp_f32_e32 v109, v109
	v_add_f32_e32 v221, v221, v108
	v_cvt_pk_bf16_f32 v106, v108, v109
	v_mfma_f32_16x16x32_bf16 v[76:79], v[228:231], v[140:143], v[76:79]
	v_exp_f32_e32 v110, v110
	v_add_f32_e32 v221, v221, v109
	v_add_f32_e32 v221, v221, v110
	v_mfma_f32_16x16x32_bf16 v[80:83], v[232:235], v[132:135], v[80:83]
	v_exp_f32_e32 v111, v111
	v_mfma_f32_16x16x32_bf16 v[88:91], v[232:235], v[140:143], v[88:91]
	v_cvt_pk_bf16_f32 v107, v110, v111
	v_exp_f32_e32 v112, v112
	v_add_f32_e32 v221, v221, v111
	v_mfma_f32_16x16x32_bf16 v[84:87], v[236:239], v[132:135], v[84:87]
	v_exp_f32_e32 v113, v113
	v_add_f32_e32 v220, v220, v112
	v_add_f32_e32 v220, v220, v113
	v_mfma_f32_16x16x32_bf16 v[92:95], v[236:239], v[140:143], v[92:95]
	v_exp_f32_e32 v114, v114
	v_cvt_pk_bf16_f32 v112, v112, v113
	v_add_f32_e32 v220, v220, v114
	ds_read_b128 v[224:227], v242 offset:8192
	ds_read_b128 v[228:231], v242 offset:10240
	ds_read_b128 v[232:235], v242 offset:12288
	ds_read_b128 v[236:239], v242 offset:14336
	s_waitcnt lgkmcnt(4)
	v_mfma_f32_16x16x32_bf16 v[0:3], v[144:147], v[96:99], v[0:3]
	v_exp_f32_e32 v115, v115
	v_exp_f32_e32 v116, v116
	v_add_f32_e32 v220, v220, v115
	v_cvt_pk_bf16_f32 v113, v114, v115
	v_mfma_f32_16x16x32_bf16 v[4:7], v[144:147], v[104:107], v[4:7]
	v_exp_f32_e32 v117, v117
	v_exp_f32_e32 v118, v118
	v_cvt_pk_bf16_f32 v114, v116, v117
	v_add_f32_e32 v220, v220, v116
	v_mfma_f32_16x16x32_bf16 v[8:11], v[148:151], v[96:99], v[8:11]
	v_exp_f32_e32 v119, v119
	v_exp_f32_e32 v120, v120
	v_cvt_pk_bf16_f32 v115, v118, v119
	v_add_f32_e32 v221, v221, v120
	v_mfma_f32_16x16x32_bf16 v[12:15], v[148:151], v[104:107], v[12:15]
	v_exp_f32_e32 v121, v121
	v_add_f32_e32 v220, v220, v117
	v_add_f32_e32 v221, v221, v121
	v_mfma_f32_16x16x32_bf16 v[16:19], v[152:155], v[96:99], v[16:19]
	v_exp_f32_e32 v122, v122
	v_cvt_pk_bf16_f32 v120, v120, v121
	v_add_f32_e32 v221, v221, v122
	v_mfma_f32_16x16x32_bf16 v[20:23], v[152:155], v[104:107], v[20:23]
	v_exp_f32_e32 v123, v123
	v_add_f32_e32 v220, v220, v118
	v_add_f32_e32 v221, v221, v123
	v_mfma_f32_16x16x32_bf16 v[24:27], v[156:159], v[96:99], v[24:27]
	v_exp_f32_e32 v124, v124
	v_cvt_pk_bf16_f32 v121, v122, v123
	v_add_f32_e32 v220, v220, v119
	v_mfma_f32_16x16x32_bf16 v[28:31], v[156:159], v[104:107], v[28:31]
	v_exp_f32_e32 v125, v125
	v_add_f32_e32 v221, v221, v124
	v_cvt_pk_bf16_f32 v122, v124, v125
	ds_read_b128 v[144:147], v243
	ds_read_b128 v[148:151], v243 offset:2048
	ds_read_b128 v[152:155], v243 offset:4096
	ds_read_b128 v[156:159], v243 offset:6144
	s_waitcnt lgkmcnt(4)
	v_mfma_f32_16x16x32_bf16 v[32:35], v[224:227], v[96:99], v[32:35]
	v_exp_f32_e32 v126, v126
	v_add_f32_e32 v221, v221, v125
	v_add_f32_e32 v221, v221, v126
	v_mfma_f32_16x16x32_bf16 v[36:39], v[224:227], v[104:107], v[36:39]
	v_exp_f32_e32 v127, v127
	v_mfma_f32_16x16x32_bf16 v[40:43], v[228:231], v[96:99], v[40:43]
	v_cvt_pk_bf16_f32 v123, v126, v127
	v_add_f32_e32 v221, v221, v127
	v_mfma_f32_16x16x32_bf16 v[44:47], v[228:231], v[104:107], v[44:47]
	v_mfma_f32_16x16x32_bf16 v[48:51], v[232:235], v[96:99], v[48:51]
	v_mfma_f32_16x16x32_bf16 v[52:55], v[232:235], v[104:107], v[52:55]
	v_mfma_f32_16x16x32_bf16 v[56:59], v[236:239], v[96:99], v[56:59]
	v_mfma_f32_16x16x32_bf16 v[60:63], v[236:239], v[104:107], v[60:63]
	ds_read_b128 v[224:227], v243 offset:8192
	ds_read_b128 v[228:231], v243 offset:10240
	ds_read_b128 v[232:235], v243 offset:12288
	ds_read_b128 v[236:239], v243 offset:14336
	s_waitcnt lgkmcnt(4)
	s_mov_b32 m0, s92
	v_mfma_f32_16x16x32_bf16 v[0:3], v[144:147], v[112:115], v[0:3]
	buffer_load_dwordx4 v205, s[28:31], s18 offen lds
	s_mov_b32 m0, s93
	v_mfma_f32_16x16x32_bf16 v[4:7], v[144:147], v[120:123], v[4:7]
	buffer_load_dwordx4 v205, s[28:31], s12 offen lds
	s_mov_b32 m0, s94
	v_mfma_f32_16x16x32_bf16 v[8:11], v[148:151], v[112:115], v[8:11]
	buffer_load_dwordx4 v206, s[36:39], s19 offen lds
	s_mov_b32 m0, s95
	v_mfma_f32_16x16x32_bf16 v[12:15], v[148:151], v[120:123], v[12:15]
	buffer_load_dwordx4 v206, s[36:39], s13 offen lds
	v_mfma_f32_16x16x32_bf16 v[16:19], v[152:155], v[112:115], v[16:19]
	v_mfma_f32_16x16x32_bf16 v[20:23], v[152:155], v[120:123], v[20:23]
	v_mfma_f32_16x16x32_bf16 v[24:27], v[156:159], v[112:115], v[24:27]
	v_mfma_f32_16x16x32_bf16 v[28:31], v[156:159], v[120:123], v[28:31]
	s_waitcnt vmcnt(4) lgkmcnt(0)
	s_barrier
	ds_read_b128 v[144:147], v217
	ds_read_b128 v[148:151], v217 offset:1024
	ds_read_b128 v[152:155], v217 offset:4096
	ds_read_b128 v[156:159], v217 offset:5120
	v_mfma_f32_16x16x32_bf16 v[32:35], v[224:227], v[112:115], v[32:35]
	v_mfma_f32_16x16x32_bf16 v[36:39], v[224:227], v[120:123], v[36:39]
	v_mfma_f32_16x16x32_bf16 v[40:43], v[228:231], v[112:115], v[40:43]
	v_mfma_f32_16x16x32_bf16 v[44:47], v[228:231], v[120:123], v[44:47]
	v_mfma_f32_16x16x32_bf16 v[48:51], v[232:235], v[112:115], v[48:51]
	v_mfma_f32_16x16x32_bf16 v[52:55], v[232:235], v[120:123], v[52:55]
	v_mfma_f32_16x16x32_bf16 v[56:59], v[236:239], v[112:115], v[56:59]
	v_mfma_f32_16x16x32_bf16 v[60:63], v[236:239], v[120:123], v[60:63]
	s_add_i32 s17, s14, 4
	s_min_u32 s17, s17, s15
	s_mul_i32 s18, s17, 0x30000
	s_lshl_b32 s19, s17, 7
	s_or_b32 s12, s18, 0x80
	s_add_i32 s13, s19, 0x200000
	ds_read_b128 v[224:227], v218
	ds_read_b128 v[228:231], v218 offset:1024
	ds_read_b128 v[232:235], v218 offset:4096
	ds_read_b128 v[236:239], v218 offset:5120
	s_waitcnt lgkmcnt(4)
	v_mfma_f32_16x16x32_bf16 v[96:99], v[144:147], v[128:131], 0
	v_exp_f32_e32 v64, v64
	v_exp_f32_e32 v65, v65
	v_add_f32_e32 v220, v220, v64
	v_add_f32_e32 v220, v220, v65
	v_mfma_f32_16x16x32_bf16 v[104:107], v[144:147], v[136:139], 0
	v_exp_f32_e32 v66, v66
	v_exp_f32_e32 v67, v67
	v_add_f32_e32 v220, v220, v66
	v_add_f32_e32 v220, v220, v67
	v_mfma_f32_16x16x32_bf16 v[100:103], v[148:151], v[128:131], 0
	v_exp_f32_e32 v68, v68
	v_exp_f32_e32 v69, v69
	v_cvt_pk_bf16_f32 v64, v64, v65
	v_add_f32_e32 v220, v220, v68
	v_mfma_f32_16x16x32_bf16 v[108:111], v[148:151], v[136:139], 0
	v_exp_f32_e32 v70, v70
	v_cvt_pk_bf16_f32 v65, v66, v67
	v_add_f32_e32 v220, v220, v69
	v_mfma_f32_16x16x32_bf16 v[112:115], v[152:155], v[128:131], 0
	v_exp_f32_e32 v71, v71
	v_cvt_pk_bf16_f32 v66, v68, v69
	v_cvt_pk_bf16_f32 v67, v70, v71
	v_mfma_f32_16x16x32_bf16 v[120:123], v[152:155], v[136:139], 0
	v_exp_f32_e32 v72, v72
	v_add_f32_e32 v220, v220, v70
	v_add_f32_e32 v221, v221, v72
	v_mfma_f32_16x16x32_bf16 v[116:119], v[156:159], v[128:131], 0
	v_exp_f32_e32 v73, v73
	v_add_f32_e32 v220, v220, v71
	v_add_f32_e32 v221, v221, v73
	v_mfma_f32_16x16x32_bf16 v[124:127], v[156:159], v[136:139], 0
	v_exp_f32_e32 v74, v74
	v_cvt_pk_bf16_f32 v72, v72, v73
	v_add_f32_e32 v221, v221, v74
	ds_read_b128 v[144:147], v242 offset:32768
	ds_read_b128 v[148:151], v242 offset:34816
	ds_read_b128 v[152:155], v242 offset:36864
	ds_read_b128 v[156:159], v242 offset:38912
	s_waitcnt lgkmcnt(4)
	v_mfma_f32_16x16x32_bf16 v[96:99], v[224:227], v[132:135], v[96:99]
	v_exp_f32_e32 v75, v75
	v_mfma_f32_16x16x32_bf16 v[104:107], v[224:227], v[140:143], v[104:107]
	v_exp_f32_e32 v76, v76
	v_add_f32_e32 v221, v221, v75
	v_cvt_pk_bf16_f32 v73, v74, v75
	v_mfma_f32_16x16x32_bf16 v[100:103], v[228:231], v[132:135], v[100:103]
	v_exp_f32_e32 v77, v77
	v_add_f32_e32 v221, v221, v76
	v_cvt_pk_bf16_f32 v74, v76, v77
	v_mfma_f32_16x16x32_bf16 v[108:111], v[228:231], v[140:143], v[108:111]
	v_exp_f32_e32 v78, v78
	v_add_f32_e32 v221, v221, v77
	v_add_f32_e32 v221, v221, v78
	v_mfma_f32_16x16x32_bf16 v[112:115], v[232:235], v[132:135], v[112:115]
	v_exp_f32_e32 v79, v79
	v_mfma_f32_16x16x32_bf16 v[120:123], v[232:235], v[140:143], v[120:123]
	v_cvt_pk_bf16_f32 v75, v78, v79
	v_exp_f32_e32 v80, v80
	v_add_f32_e32 v221, v221, v79
	v_mfma_f32_16x16x32_bf16 v[116:119], v[236:239], v[132:135], v[116:119]
	v_exp_f32_e32 v81, v81
	v_add_f32_e32 v220, v220, v80
	v_add_f32_e32 v220, v220, v81
	v_mfma_f32_16x16x32_bf16 v[124:127], v[236:239], v[140:143], v[124:127]
	v_exp_f32_e32 v82, v82
	v_cvt_pk_bf16_f32 v80, v80, v81
	v_add_f32_e32 v220, v220, v82
	ds_read_b128 v[224:227], v242 offset:40960
	ds_read_b128 v[228:231], v242 offset:43008
	ds_read_b128 v[232:235], v242 offset:45056
	ds_read_b128 v[236:239], v242 offset:47104
	s_waitcnt lgkmcnt(4)
	v_mfma_f32_16x16x32_bf16 v[0:3], v[144:147], v[64:67], v[0:3]
	v_exp_f32_e32 v83, v83
	v_exp_f32_e32 v84, v84
	v_add_f32_e32 v220, v220, v83
	v_cvt_pk_bf16_f32 v81, v82, v83
	v_mfma_f32_16x16x32_bf16 v[4:7], v[144:147], v[72:75], v[4:7]
	v_exp_f32_e32 v85, v85
	v_exp_f32_e32 v86, v86
	v_cvt_pk_bf16_f32 v82, v84, v85
	v_add_f32_e32 v220, v220, v84
	v_mfma_f32_16x16x32_bf16 v[8:11], v[148:151], v[64:67], v[8:11]
	v_exp_f32_e32 v87, v87
	v_exp_f32_e32 v88, v88
	v_cvt_pk_bf16_f32 v83, v86, v87
	v_add_f32_e32 v221, v221, v88
	v_mfma_f32_16x16x32_bf16 v[12:15], v[148:151], v[72:75], v[12:15]
	v_exp_f32_e32 v89, v89
	v_add_f32_e32 v220, v220, v85
	v_add_f32_e32 v221, v221, v89
	v_mfma_f32_16x16x32_bf16 v[16:19], v[152:155], v[64:67], v[16:19]
	v_exp_f32_e32 v90, v90
	v_cvt_pk_bf16_f32 v88, v88, v89
	v_add_f32_e32 v221, v221, v90
	v_mfma_f32_16x16x32_bf16 v[20:23], v[152:155], v[72:75], v[20:23]
	v_exp_f32_e32 v91, v91
	v_add_f32_e32 v220, v220, v86
	v_add_f32_e32 v221, v221, v91
	v_mfma_f32_16x16x32_bf16 v[24:27], v[156:159], v[64:67], v[24:27]
	v_exp_f32_e32 v92, v92
	v_cvt_pk_bf16_f32 v89, v90, v91
	v_add_f32_e32 v220, v220, v87
	v_mfma_f32_16x16x32_bf16 v[28:31], v[156:159], v[72:75], v[28:31]
	v_exp_f32_e32 v93, v93
	v_add_f32_e32 v221, v221, v92
	v_cvt_pk_bf16_f32 v90, v92, v93
	ds_read_b128 v[144:147], v243 offset:32768
	ds_read_b128 v[148:151], v243 offset:34816
	ds_read_b128 v[152:155], v243 offset:36864
	ds_read_b128 v[156:159], v243 offset:38912
	s_waitcnt lgkmcnt(4)
	v_mfma_f32_16x16x32_bf16 v[32:35], v[224:227], v[64:67], v[32:35]
	v_exp_f32_e32 v94, v94
	v_add_f32_e32 v221, v221, v93
	v_add_f32_e32 v221, v221, v94
	v_mfma_f32_16x16x32_bf16 v[36:39], v[224:227], v[72:75], v[36:39]
	v_exp_f32_e32 v95, v95
	v_mfma_f32_16x16x32_bf16 v[40:43], v[228:231], v[64:67], v[40:43]
	v_cvt_pk_bf16_f32 v91, v94, v95
	v_add_f32_e32 v221, v221, v95
	v_mfma_f32_16x16x32_bf16 v[44:47], v[228:231], v[72:75], v[44:47]
	v_mfma_f32_16x16x32_bf16 v[48:51], v[232:235], v[64:67], v[48:51]
	v_mfma_f32_16x16x32_bf16 v[52:55], v[232:235], v[72:75], v[52:55]
	v_mfma_f32_16x16x32_bf16 v[56:59], v[236:239], v[64:67], v[56:59]
	v_mfma_f32_16x16x32_bf16 v[60:63], v[236:239], v[72:75], v[60:63]
	ds_read_b128 v[224:227], v243 offset:40960
	ds_read_b128 v[228:231], v243 offset:43008
	ds_read_b128 v[232:235], v243 offset:45056
	ds_read_b128 v[236:239], v243 offset:47104
	s_waitcnt lgkmcnt(4)
	s_mov_b32 m0, s72
	v_mfma_f32_16x16x32_bf16 v[0:3], v[144:147], v[80:83], v[0:3]
	buffer_load_dwordx4 v205, s[28:31], s18 offen lds
	s_mov_b32 m0, s73
	v_mfma_f32_16x16x32_bf16 v[4:7], v[144:147], v[88:91], v[4:7]
	buffer_load_dwordx4 v205, s[28:31], s12 offen lds
	s_mov_b32 m0, s6
	v_mfma_f32_16x16x32_bf16 v[8:11], v[148:151], v[80:83], v[8:11]
	buffer_load_dwordx4 v206, s[36:39], s19 offen lds
	s_mov_b32 m0, s7
	v_mfma_f32_16x16x32_bf16 v[12:15], v[148:151], v[88:91], v[12:15]
	buffer_load_dwordx4 v206, s[36:39], s13 offen lds
	v_mfma_f32_16x16x32_bf16 v[16:19], v[152:155], v[80:83], v[16:19]
	v_mfma_f32_16x16x32_bf16 v[20:23], v[152:155], v[88:91], v[20:23]
	v_mfma_f32_16x16x32_bf16 v[24:27], v[156:159], v[80:83], v[24:27]
	v_mfma_f32_16x16x32_bf16 v[28:31], v[156:159], v[88:91], v[28:31]
	s_waitcnt vmcnt(4) lgkmcnt(0)
	s_barrier
	ds_read_b128 v[144:147], v217 offset:32768
	ds_read_b128 v[148:151], v217 offset:33792
	ds_read_b128 v[152:155], v217 offset:36864
	ds_read_b128 v[156:159], v217 offset:37888
	v_mfma_f32_16x16x32_bf16 v[32:35], v[224:227], v[80:83], v[32:35]
	v_mfma_f32_16x16x32_bf16 v[36:39], v[224:227], v[88:91], v[36:39]
	v_mfma_f32_16x16x32_bf16 v[40:43], v[228:231], v[80:83], v[40:43]
	v_mfma_f32_16x16x32_bf16 v[44:47], v[228:231], v[88:91], v[44:47]
	v_mfma_f32_16x16x32_bf16 v[48:51], v[232:235], v[80:83], v[48:51]
	v_mfma_f32_16x16x32_bf16 v[52:55], v[232:235], v[88:91], v[52:55]
	v_mfma_f32_16x16x32_bf16 v[56:59], v[236:239], v[80:83], v[56:59]
	v_mfma_f32_16x16x32_bf16 v[60:63], v[236:239], v[88:91], v[60:63]
	s_add_i32 s17, s14, 5
	s_min_u32 s17, s17, s15
	s_mul_i32 s18, s17, 0x30000
	s_lshl_b32 s19, s17, 7
	s_or_b32 s12, s18, 0x80
	s_add_i32 s13, s19, 0x200000
	ds_read_b128 v[224:227], v218 offset:32768
	ds_read_b128 v[228:231], v218 offset:33792
	ds_read_b128 v[232:235], v218 offset:36864
	ds_read_b128 v[236:239], v218 offset:37888
	s_waitcnt lgkmcnt(4)
	v_mfma_f32_16x16x32_bf16 v[64:67], v[144:147], v[128:131], 0
	v_exp_f32_e32 v96, v96
	v_exp_f32_e32 v97, v97
	v_add_f32_e32 v220, v220, v96
	v_add_f32_e32 v220, v220, v97
	v_mfma_f32_16x16x32_bf16 v[72:75], v[144:147], v[136:139], 0
	v_exp_f32_e32 v98, v98
	v_exp_f32_e32 v99, v99
	v_add_f32_e32 v220, v220, v98
	v_add_f32_e32 v220, v220, v99
	v_mfma_f32_16x16x32_bf16 v[68:71], v[148:151], v[128:131], 0
	v_exp_f32_e32 v100, v100
	v_exp_f32_e32 v101, v101
	v_cvt_pk_bf16_f32 v96, v96, v97
	v_add_f32_e32 v220, v220, v100
	v_mfma_f32_16x16x32_bf16 v[76:79], v[148:151], v[136:139], 0
	v_exp_f32_e32 v102, v102
	v_cvt_pk_bf16_f32 v97, v98, v99
	v_add_f32_e32 v220, v220, v101
	v_mfma_f32_16x16x32_bf16 v[80:83], v[152:155], v[128:131], 0
	v_exp_f32_e32 v103, v103
	v_cvt_pk_bf16_f32 v98, v100, v101
	v_cvt_pk_bf16_f32 v99, v102, v103
	v_mfma_f32_16x16x32_bf16 v[88:91], v[152:155], v[136:139], 0
	v_exp_f32_e32 v104, v104
	v_add_f32_e32 v220, v220, v102
	v_add_f32_e32 v221, v221, v104
	v_mfma_f32_16x16x32_bf16 v[84:87], v[156:159], v[128:131], 0
	v_exp_f32_e32 v105, v105
	v_add_f32_e32 v220, v220, v103
	v_add_f32_e32 v221, v221, v105
	v_mfma_f32_16x16x32_bf16 v[92:95], v[156:159], v[136:139], 0
	v_exp_f32_e32 v106, v106
	v_cvt_pk_bf16_f32 v104, v104, v105
	v_add_f32_e32 v221, v221, v106
	ds_read_b128 v[144:147], v244
	ds_read_b128 v[148:151], v244 offset:2048
	ds_read_b128 v[152:155], v244 offset:4096
	ds_read_b128 v[156:159], v244 offset:6144
	s_waitcnt lgkmcnt(4)
	v_mfma_f32_16x16x32_bf16 v[64:67], v[224:227], v[132:135], v[64:67]
	v_exp_f32_e32 v107, v107
	v_mfma_f32_16x16x32_bf16 v[72:75], v[224:227], v[140:143], v[72:75]
	v_exp_f32_e32 v108, v108
	v_add_f32_e32 v221, v221, v107
	v_cvt_pk_bf16_f32 v105, v106, v107
	v_mfma_f32_16x16x32_bf16 v[68:71], v[228:231], v[132:135], v[68:71]
	v_exp_f32_e32 v109, v109
	v_add_f32_e32 v221, v221, v108
	v_cvt_pk_bf16_f32 v106, v108, v109
	v_mfma_f32_16x16x32_bf16 v[76:79], v[228:231], v[140:143], v[76:79]
	v_exp_f32_e32 v110, v110
	v_add_f32_e32 v221, v221, v109
	v_add_f32_e32 v221, v221, v110
	v_mfma_f32_16x16x32_bf16 v[80:83], v[232:235], v[132:135], v[80:83]
	v_exp_f32_e32 v111, v111
	v_mfma_f32_16x16x32_bf16 v[88:91], v[232:235], v[140:143], v[88:91]
	v_cvt_pk_bf16_f32 v107, v110, v111
	v_exp_f32_e32 v112, v112
	v_add_f32_e32 v221, v221, v111
	v_mfma_f32_16x16x32_bf16 v[84:87], v[236:239], v[132:135], v[84:87]
	v_exp_f32_e32 v113, v113
	v_add_f32_e32 v220, v220, v112
	v_add_f32_e32 v220, v220, v113
	v_mfma_f32_16x16x32_bf16 v[92:95], v[236:239], v[140:143], v[92:95]
	v_exp_f32_e32 v114, v114
	v_cvt_pk_bf16_f32 v112, v112, v113
	v_add_f32_e32 v220, v220, v114
	ds_read_b128 v[224:227], v244 offset:8192
	ds_read_b128 v[228:231], v244 offset:10240
	ds_read_b128 v[232:235], v244 offset:12288
	ds_read_b128 v[236:239], v244 offset:14336
	s_waitcnt lgkmcnt(4)
	v_mfma_f32_16x16x32_bf16 v[0:3], v[144:147], v[96:99], v[0:3]
	v_exp_f32_e32 v115, v115
	v_exp_f32_e32 v116, v116
	v_add_f32_e32 v220, v220, v115
	v_cvt_pk_bf16_f32 v113, v114, v115
	v_mfma_f32_16x16x32_bf16 v[4:7], v[144:147], v[104:107], v[4:7]
	v_exp_f32_e32 v117, v117
	v_exp_f32_e32 v118, v118
	v_cvt_pk_bf16_f32 v114, v116, v117
	v_add_f32_e32 v220, v220, v116
	v_mfma_f32_16x16x32_bf16 v[8:11], v[148:151], v[96:99], v[8:11]
	v_exp_f32_e32 v119, v119
	v_exp_f32_e32 v120, v120
	v_cvt_pk_bf16_f32 v115, v118, v119
	v_add_f32_e32 v221, v221, v120
	v_mfma_f32_16x16x32_bf16 v[12:15], v[148:151], v[104:107], v[12:15]
	v_exp_f32_e32 v121, v121
	v_add_f32_e32 v220, v220, v117
	v_add_f32_e32 v221, v221, v121
	v_mfma_f32_16x16x32_bf16 v[16:19], v[152:155], v[96:99], v[16:19]
	v_exp_f32_e32 v122, v122
	v_cvt_pk_bf16_f32 v120, v120, v121
	v_add_f32_e32 v221, v221, v122
	v_mfma_f32_16x16x32_bf16 v[20:23], v[152:155], v[104:107], v[20:23]
	v_exp_f32_e32 v123, v123
	v_add_f32_e32 v220, v220, v118
	v_add_f32_e32 v221, v221, v123
	v_mfma_f32_16x16x32_bf16 v[24:27], v[156:159], v[96:99], v[24:27]
	v_exp_f32_e32 v124, v124
	v_cvt_pk_bf16_f32 v121, v122, v123
	v_add_f32_e32 v220, v220, v119
	v_mfma_f32_16x16x32_bf16 v[28:31], v[156:159], v[104:107], v[28:31]
	v_exp_f32_e32 v125, v125
	v_add_f32_e32 v221, v221, v124
	v_cvt_pk_bf16_f32 v122, v124, v125
	ds_read_b128 v[144:147], v245
	ds_read_b128 v[148:151], v245 offset:2048
	ds_read_b128 v[152:155], v245 offset:4096
	ds_read_b128 v[156:159], v245 offset:6144
	s_waitcnt lgkmcnt(4)
	v_mfma_f32_16x16x32_bf16 v[32:35], v[224:227], v[96:99], v[32:35]
	v_exp_f32_e32 v126, v126
	v_add_f32_e32 v221, v221, v125
	v_add_f32_e32 v221, v221, v126
	v_mfma_f32_16x16x32_bf16 v[36:39], v[224:227], v[104:107], v[36:39]
	v_exp_f32_e32 v127, v127
	v_mfma_f32_16x16x32_bf16 v[40:43], v[228:231], v[96:99], v[40:43]
	v_cvt_pk_bf16_f32 v123, v126, v127
	v_add_f32_e32 v221, v221, v127
	v_mfma_f32_16x16x32_bf16 v[44:47], v[228:231], v[104:107], v[44:47]
	v_mfma_f32_16x16x32_bf16 v[48:51], v[232:235], v[96:99], v[48:51]
	v_mfma_f32_16x16x32_bf16 v[52:55], v[232:235], v[104:107], v[52:55]
	v_mfma_f32_16x16x32_bf16 v[56:59], v[236:239], v[96:99], v[56:59]
	v_mfma_f32_16x16x32_bf16 v[60:63], v[236:239], v[104:107], v[60:63]
	ds_read_b128 v[224:227], v245 offset:8192
	ds_read_b128 v[228:231], v245 offset:10240
	ds_read_b128 v[232:235], v245 offset:12288
	ds_read_b128 v[236:239], v245 offset:14336
	s_waitcnt lgkmcnt(4)
	s_mov_b32 m0, s8
	v_mfma_f32_16x16x32_bf16 v[0:3], v[144:147], v[112:115], v[0:3]
	buffer_load_dwordx4 v205, s[28:31], s18 offen lds
	s_mov_b32 m0, s9
	v_mfma_f32_16x16x32_bf16 v[4:7], v[144:147], v[120:123], v[4:7]
	buffer_load_dwordx4 v205, s[28:31], s12 offen lds
	s_mov_b32 m0, s58
	v_mfma_f32_16x16x32_bf16 v[8:11], v[148:151], v[112:115], v[8:11]
	buffer_load_dwordx4 v206, s[36:39], s19 offen lds
	s_mov_b32 m0, s79
	v_mfma_f32_16x16x32_bf16 v[12:15], v[148:151], v[120:123], v[12:15]
	buffer_load_dwordx4 v206, s[36:39], s13 offen lds
	v_mfma_f32_16x16x32_bf16 v[16:19], v[152:155], v[112:115], v[16:19]
	v_mfma_f32_16x16x32_bf16 v[20:23], v[152:155], v[120:123], v[20:23]
	v_mfma_f32_16x16x32_bf16 v[24:27], v[156:159], v[112:115], v[24:27]
	v_mfma_f32_16x16x32_bf16 v[28:31], v[156:159], v[120:123], v[28:31]
	s_waitcnt vmcnt(4) lgkmcnt(0)
	s_barrier
	ds_read_b128 v[144:147], v240
	ds_read_b128 v[148:151], v240 offset:1024
	ds_read_b128 v[152:155], v240 offset:4096
	ds_read_b128 v[156:159], v240 offset:5120
	v_mfma_f32_16x16x32_bf16 v[32:35], v[224:227], v[112:115], v[32:35]
	v_mfma_f32_16x16x32_bf16 v[36:39], v[224:227], v[120:123], v[36:39]
	v_mfma_f32_16x16x32_bf16 v[40:43], v[228:231], v[112:115], v[40:43]
	v_mfma_f32_16x16x32_bf16 v[44:47], v[228:231], v[120:123], v[44:47]
	v_mfma_f32_16x16x32_bf16 v[48:51], v[232:235], v[112:115], v[48:51]
	v_mfma_f32_16x16x32_bf16 v[52:55], v[232:235], v[120:123], v[52:55]
	v_mfma_f32_16x16x32_bf16 v[56:59], v[236:239], v[112:115], v[56:59]
	v_mfma_f32_16x16x32_bf16 v[60:63], v[236:239], v[120:123], v[60:63]
	s_add_i32 s17, s14, 6
	s_min_u32 s17, s17, s15
	s_mul_i32 s18, s17, 0x30000
	s_lshl_b32 s19, s17, 7
	s_or_b32 s12, s18, 0x80
	s_add_i32 s13, s19, 0x200000
	ds_read_b128 v[224:227], v241
	ds_read_b128 v[228:231], v241 offset:1024
	ds_read_b128 v[232:235], v241 offset:4096
	ds_read_b128 v[236:239], v241 offset:5120
	s_waitcnt lgkmcnt(4)
	v_mfma_f32_16x16x32_bf16 v[96:99], v[144:147], v[128:131], 0
	v_exp_f32_e32 v64, v64
	v_exp_f32_e32 v65, v65
	v_add_f32_e32 v220, v220, v64
	v_add_f32_e32 v220, v220, v65
	v_mfma_f32_16x16x32_bf16 v[104:107], v[144:147], v[136:139], 0
	v_exp_f32_e32 v66, v66
	v_exp_f32_e32 v67, v67
	v_add_f32_e32 v220, v220, v66
	v_add_f32_e32 v220, v220, v67
	v_mfma_f32_16x16x32_bf16 v[100:103], v[148:151], v[128:131], 0
	v_exp_f32_e32 v68, v68
	v_exp_f32_e32 v69, v69
	v_cvt_pk_bf16_f32 v64, v64, v65
	v_add_f32_e32 v220, v220, v68
	v_mfma_f32_16x16x32_bf16 v[108:111], v[148:151], v[136:139], 0
	v_exp_f32_e32 v70, v70
	v_cvt_pk_bf16_f32 v65, v66, v67
	v_add_f32_e32 v220, v220, v69
	v_mfma_f32_16x16x32_bf16 v[112:115], v[152:155], v[128:131], 0
	v_exp_f32_e32 v71, v71
	v_cvt_pk_bf16_f32 v66, v68, v69
	v_cvt_pk_bf16_f32 v67, v70, v71
	v_mfma_f32_16x16x32_bf16 v[120:123], v[152:155], v[136:139], 0
	v_exp_f32_e32 v72, v72
	v_add_f32_e32 v220, v220, v70
	v_add_f32_e32 v221, v221, v72
	v_mfma_f32_16x16x32_bf16 v[116:119], v[156:159], v[128:131], 0
	v_exp_f32_e32 v73, v73
	v_add_f32_e32 v220, v220, v71
	v_add_f32_e32 v221, v221, v73
	v_mfma_f32_16x16x32_bf16 v[124:127], v[156:159], v[136:139], 0
	v_exp_f32_e32 v74, v74
	v_cvt_pk_bf16_f32 v72, v72, v73
	v_add_f32_e32 v221, v221, v74
	ds_read_b128 v[144:147], v244 offset:32768
	ds_read_b128 v[148:151], v244 offset:34816
	ds_read_b128 v[152:155], v244 offset:36864
	ds_read_b128 v[156:159], v244 offset:38912
	s_waitcnt lgkmcnt(4)
	v_mfma_f32_16x16x32_bf16 v[96:99], v[224:227], v[132:135], v[96:99]
	v_exp_f32_e32 v75, v75
	v_mfma_f32_16x16x32_bf16 v[104:107], v[224:227], v[140:143], v[104:107]
	v_exp_f32_e32 v76, v76
	v_add_f32_e32 v221, v221, v75
	v_cvt_pk_bf16_f32 v73, v74, v75
	v_mfma_f32_16x16x32_bf16 v[100:103], v[228:231], v[132:135], v[100:103]
	v_exp_f32_e32 v77, v77
	v_add_f32_e32 v221, v221, v76
	v_cvt_pk_bf16_f32 v74, v76, v77
	v_mfma_f32_16x16x32_bf16 v[108:111], v[228:231], v[140:143], v[108:111]
	v_exp_f32_e32 v78, v78
	v_add_f32_e32 v221, v221, v77
	v_add_f32_e32 v221, v221, v78
	v_mfma_f32_16x16x32_bf16 v[112:115], v[232:235], v[132:135], v[112:115]
	v_exp_f32_e32 v79, v79
	v_mfma_f32_16x16x32_bf16 v[120:123], v[232:235], v[140:143], v[120:123]
	v_cvt_pk_bf16_f32 v75, v78, v79
	v_exp_f32_e32 v80, v80
	v_add_f32_e32 v221, v221, v79
	v_mfma_f32_16x16x32_bf16 v[116:119], v[236:239], v[132:135], v[116:119]
	v_exp_f32_e32 v81, v81
	v_add_f32_e32 v220, v220, v80
	v_add_f32_e32 v220, v220, v81
	v_mfma_f32_16x16x32_bf16 v[124:127], v[236:239], v[140:143], v[124:127]
	v_exp_f32_e32 v82, v82
	v_cvt_pk_bf16_f32 v80, v80, v81
	v_add_f32_e32 v220, v220, v82
	ds_read_b128 v[224:227], v244 offset:40960
	ds_read_b128 v[228:231], v244 offset:43008
	ds_read_b128 v[232:235], v244 offset:45056
	ds_read_b128 v[236:239], v244 offset:47104
	s_waitcnt lgkmcnt(4)
	v_mfma_f32_16x16x32_bf16 v[0:3], v[144:147], v[64:67], v[0:3]
	v_exp_f32_e32 v83, v83
	v_exp_f32_e32 v84, v84
	v_add_f32_e32 v220, v220, v83
	v_cvt_pk_bf16_f32 v81, v82, v83
	v_mfma_f32_16x16x32_bf16 v[4:7], v[144:147], v[72:75], v[4:7]
	v_exp_f32_e32 v85, v85
	v_exp_f32_e32 v86, v86
	v_cvt_pk_bf16_f32 v82, v84, v85
	v_add_f32_e32 v220, v220, v84
	v_mfma_f32_16x16x32_bf16 v[8:11], v[148:151], v[64:67], v[8:11]
	v_exp_f32_e32 v87, v87
	v_exp_f32_e32 v88, v88
	v_cvt_pk_bf16_f32 v83, v86, v87
	v_add_f32_e32 v221, v221, v88
	v_mfma_f32_16x16x32_bf16 v[12:15], v[148:151], v[72:75], v[12:15]
	v_exp_f32_e32 v89, v89
	v_add_f32_e32 v220, v220, v85
	v_add_f32_e32 v221, v221, v89
	v_mfma_f32_16x16x32_bf16 v[16:19], v[152:155], v[64:67], v[16:19]
	v_exp_f32_e32 v90, v90
	v_cvt_pk_bf16_f32 v88, v88, v89
	v_add_f32_e32 v221, v221, v90
	v_mfma_f32_16x16x32_bf16 v[20:23], v[152:155], v[72:75], v[20:23]
	v_exp_f32_e32 v91, v91
	v_add_f32_e32 v220, v220, v86
	v_add_f32_e32 v221, v221, v91
	v_mfma_f32_16x16x32_bf16 v[24:27], v[156:159], v[64:67], v[24:27]
	v_exp_f32_e32 v92, v92
	v_cvt_pk_bf16_f32 v89, v90, v91
	v_add_f32_e32 v220, v220, v87
	v_mfma_f32_16x16x32_bf16 v[28:31], v[156:159], v[72:75], v[28:31]
	v_exp_f32_e32 v93, v93
	v_add_f32_e32 v221, v221, v92
	v_cvt_pk_bf16_f32 v90, v92, v93
	ds_read_b128 v[144:147], v245 offset:32768
	ds_read_b128 v[148:151], v245 offset:34816
	ds_read_b128 v[152:155], v245 offset:36864
	ds_read_b128 v[156:159], v245 offset:38912
	s_waitcnt lgkmcnt(4)
	v_mfma_f32_16x16x32_bf16 v[32:35], v[224:227], v[64:67], v[32:35]
	v_exp_f32_e32 v94, v94
	v_add_f32_e32 v221, v221, v93
	v_add_f32_e32 v221, v221, v94
	v_mfma_f32_16x16x32_bf16 v[36:39], v[224:227], v[72:75], v[36:39]
	v_exp_f32_e32 v95, v95
	v_mfma_f32_16x16x32_bf16 v[40:43], v[228:231], v[64:67], v[40:43]
	v_cvt_pk_bf16_f32 v91, v94, v95
	v_add_f32_e32 v221, v221, v95
	v_mfma_f32_16x16x32_bf16 v[44:47], v[228:231], v[72:75], v[44:47]
	v_mfma_f32_16x16x32_bf16 v[48:51], v[232:235], v[64:67], v[48:51]
	v_mfma_f32_16x16x32_bf16 v[52:55], v[232:235], v[72:75], v[52:55]
	v_mfma_f32_16x16x32_bf16 v[56:59], v[236:239], v[64:67], v[56:59]
	v_mfma_f32_16x16x32_bf16 v[60:63], v[236:239], v[72:75], v[60:63]
	ds_read_b128 v[224:227], v245 offset:40960
	ds_read_b128 v[228:231], v245 offset:43008
	ds_read_b128 v[232:235], v245 offset:45056
	ds_read_b128 v[236:239], v245 offset:47104
	s_waitcnt lgkmcnt(4)
	s_mov_b32 m0, s52
	v_mfma_f32_16x16x32_bf16 v[0:3], v[144:147], v[80:83], v[0:3]
	buffer_load_dwordx4 v205, s[28:31], s18 offen lds
	s_mov_b32 m0, s53
	v_mfma_f32_16x16x32_bf16 v[4:7], v[144:147], v[88:91], v[4:7]
	buffer_load_dwordx4 v205, s[28:31], s12 offen lds
	s_mov_b32 m0, s90
	v_mfma_f32_16x16x32_bf16 v[8:11], v[148:151], v[80:83], v[8:11]
	buffer_load_dwordx4 v206, s[36:39], s19 offen lds
	s_mov_b32 m0, s91
	v_mfma_f32_16x16x32_bf16 v[12:15], v[148:151], v[88:91], v[12:15]
	buffer_load_dwordx4 v206, s[36:39], s13 offen lds
	v_mfma_f32_16x16x32_bf16 v[16:19], v[152:155], v[80:83], v[16:19]
	v_mfma_f32_16x16x32_bf16 v[20:23], v[152:155], v[88:91], v[20:23]
	v_mfma_f32_16x16x32_bf16 v[24:27], v[156:159], v[80:83], v[24:27]
	v_mfma_f32_16x16x32_bf16 v[28:31], v[156:159], v[88:91], v[28:31]
	s_waitcnt vmcnt(4) lgkmcnt(0)
	s_barrier
	ds_read_b128 v[144:147], v240 offset:32768
	ds_read_b128 v[148:151], v240 offset:33792
	ds_read_b128 v[152:155], v240 offset:36864
	ds_read_b128 v[156:159], v240 offset:37888
	v_mfma_f32_16x16x32_bf16 v[32:35], v[224:227], v[80:83], v[32:35]
	v_mfma_f32_16x16x32_bf16 v[36:39], v[224:227], v[88:91], v[36:39]
	v_mfma_f32_16x16x32_bf16 v[40:43], v[228:231], v[80:83], v[40:43]
	v_mfma_f32_16x16x32_bf16 v[44:47], v[228:231], v[88:91], v[44:47]
	v_mfma_f32_16x16x32_bf16 v[48:51], v[232:235], v[80:83], v[48:51]
	v_mfma_f32_16x16x32_bf16 v[52:55], v[232:235], v[88:91], v[52:55]
	v_mfma_f32_16x16x32_bf16 v[56:59], v[236:239], v[80:83], v[56:59]
	v_mfma_f32_16x16x32_bf16 v[60:63], v[236:239], v[88:91], v[60:63]
	s_add_i32 s14, s14, 4
	s_add_i32 s17, s14, 4
	s_cmp_le_u32 s17, s16
	s_cbranch_scc1 .La16_main
.La16_rem_check:
	s_cmp_ge_u32 s14, s16
	s_cbranch_scc1 .La16_tail01
	s_add_i32 s17, s14, 3
	s_min_u32 s17, s17, s15
	s_mul_i32 s18, s17, 0x30000
	s_lshl_b32 s19, s17, 7
	s_or_b32 s12, s18, 0x80
	s_add_i32 s13, s19, 0x200000
	ds_read_b128 v[224:227], v241 offset:32768
	ds_read_b128 v[228:231], v241 offset:33792
	ds_read_b128 v[232:235], v241 offset:36864
	ds_read_b128 v[236:239], v241 offset:37888
	s_waitcnt lgkmcnt(4)
	v_mfma_f32_16x16x32_bf16 v[64:67], v[144:147], v[128:131], 0
	v_exp_f32_e32 v96, v96
	v_exp_f32_e32 v97, v97
	v_add_f32_e32 v220, v220, v96
	v_add_f32_e32 v220, v220, v97
	v_mfma_f32_16x16x32_bf16 v[72:75], v[144:147], v[136:139], 0
	v_exp_f32_e32 v98, v98
	v_exp_f32_e32 v99, v99
	v_add_f32_e32 v220, v220, v98
	v_add_f32_e32 v220, v220, v99
	v_mfma_f32_16x16x32_bf16 v[68:71], v[148:151], v[128:131], 0
	v_exp_f32_e32 v100, v100
	v_exp_f32_e32 v101, v101
	v_cvt_pk_bf16_f32 v96, v96, v97
	v_add_f32_e32 v220, v220, v100
	v_mfma_f32_16x16x32_bf16 v[76:79], v[148:151], v[136:139], 0
	v_exp_f32_e32 v102, v102
	v_cvt_pk_bf16_f32 v97, v98, v99
	v_add_f32_e32 v220, v220, v101
	v_mfma_f32_16x16x32_bf16 v[80:83], v[152:155], v[128:131], 0
	v_exp_f32_e32 v103, v103
	v_cvt_pk_bf16_f32 v98, v100, v101
	v_cvt_pk_bf16_f32 v99, v102, v103
	v_mfma_f32_16x16x32_bf16 v[88:91], v[152:155], v[136:139], 0
	v_exp_f32_e32 v104, v104
	v_add_f32_e32 v220, v220, v102
	v_add_f32_e32 v221, v221, v104
	v_mfma_f32_16x16x32_bf16 v[84:87], v[156:159], v[128:131], 0
	v_exp_f32_e32 v105, v105
	v_add_f32_e32 v220, v220, v103
	v_add_f32_e32 v221, v221, v105
	v_mfma_f32_16x16x32_bf16 v[92:95], v[156:159], v[136:139], 0
	v_exp_f32_e32 v106, v106
	v_cvt_pk_bf16_f32 v104, v104, v105
	v_add_f32_e32 v221, v221, v106
	ds_read_b128 v[144:147], v242
	ds_read_b128 v[148:151], v242 offset:2048
	ds_read_b128 v[152:155], v242 offset:4096
	ds_read_b128 v[156:159], v242 offset:6144
	s_waitcnt lgkmcnt(4)
	v_mfma_f32_16x16x32_bf16 v[64:67], v[224:227], v[132:135], v[64:67]
	v_exp_f32_e32 v107, v107
	v_mfma_f32_16x16x32_bf16 v[72:75], v[224:227], v[140:143], v[72:75]
	v_exp_f32_e32 v108, v108
	v_add_f32_e32 v221, v221, v107
	v_cvt_pk_bf16_f32 v105, v106, v107
	v_mfma_f32_16x16x32_bf16 v[68:71], v[228:231], v[132:135], v[68:71]
	v_exp_f32_e32 v109, v109
	v_add_f32_e32 v221, v221, v108
	v_cvt_pk_bf16_f32 v106, v108, v109
	v_mfma_f32_16x16x32_bf16 v[76:79], v[228:231], v[140:143], v[76:79]
	v_exp_f32_e32 v110, v110
	v_add_f32_e32 v221, v221, v109
	v_add_f32_e32 v221, v221, v110
	v_mfma_f32_16x16x32_bf16 v[80:83], v[232:235], v[132:135], v[80:83]
	v_exp_f32_e32 v111, v111
	v_mfma_f32_16x16x32_bf16 v[88:91], v[232:235], v[140:143], v[88:91]
	v_cvt_pk_bf16_f32 v107, v110, v111
	v_exp_f32_e32 v112, v112
	v_add_f32_e32 v221, v221, v111
	v_mfma_f32_16x16x32_bf16 v[84:87], v[236:239], v[132:135], v[84:87]
	v_exp_f32_e32 v113, v113
	v_add_f32_e32 v220, v220, v112
	v_add_f32_e32 v220, v220, v113
	v_mfma_f32_16x16x32_bf16 v[92:95], v[236:239], v[140:143], v[92:95]
	v_exp_f32_e32 v114, v114
	v_cvt_pk_bf16_f32 v112, v112, v113
	v_add_f32_e32 v220, v220, v114
	ds_read_b128 v[224:227], v242 offset:8192
	ds_read_b128 v[228:231], v242 offset:10240
	ds_read_b128 v[232:235], v242 offset:12288
	ds_read_b128 v[236:239], v242 offset:14336
	s_waitcnt lgkmcnt(4)
	v_mfma_f32_16x16x32_bf16 v[0:3], v[144:147], v[96:99], v[0:3]
	v_exp_f32_e32 v115, v115
	v_exp_f32_e32 v116, v116
	v_add_f32_e32 v220, v220, v115
	v_cvt_pk_bf16_f32 v113, v114, v115
	v_mfma_f32_16x16x32_bf16 v[4:7], v[144:147], v[104:107], v[4:7]
	v_exp_f32_e32 v117, v117
	v_exp_f32_e32 v118, v118
	v_cvt_pk_bf16_f32 v114, v116, v117
	v_add_f32_e32 v220, v220, v116
	v_mfma_f32_16x16x32_bf16 v[8:11], v[148:151], v[96:99], v[8:11]
	v_exp_f32_e32 v119, v119
	v_exp_f32_e32 v120, v120
	v_cvt_pk_bf16_f32 v115, v118, v119
	v_add_f32_e32 v221, v221, v120
	v_mfma_f32_16x16x32_bf16 v[12:15], v[148:151], v[104:107], v[12:15]
	v_exp_f32_e32 v121, v121
	v_add_f32_e32 v220, v220, v117
	v_add_f32_e32 v221, v221, v121
	v_mfma_f32_16x16x32_bf16 v[16:19], v[152:155], v[96:99], v[16:19]
	v_exp_f32_e32 v122, v122
	v_cvt_pk_bf16_f32 v120, v120, v121
	v_add_f32_e32 v221, v221, v122
	v_mfma_f32_16x16x32_bf16 v[20:23], v[152:155], v[104:107], v[20:23]
	v_exp_f32_e32 v123, v123
	v_add_f32_e32 v220, v220, v118
	v_add_f32_e32 v221, v221, v123
	v_mfma_f32_16x16x32_bf16 v[24:27], v[156:159], v[96:99], v[24:27]
	v_exp_f32_e32 v124, v124
	v_cvt_pk_bf16_f32 v121, v122, v123
	v_add_f32_e32 v220, v220, v119
	v_mfma_f32_16x16x32_bf16 v[28:31], v[156:159], v[104:107], v[28:31]
	v_exp_f32_e32 v125, v125
	v_add_f32_e32 v221, v221, v124
	v_cvt_pk_bf16_f32 v122, v124, v125
	ds_read_b128 v[144:147], v243
	ds_read_b128 v[148:151], v243 offset:2048
	ds_read_b128 v[152:155], v243 offset:4096
	ds_read_b128 v[156:159], v243 offset:6144
	s_waitcnt lgkmcnt(4)
	v_mfma_f32_16x16x32_bf16 v[32:35], v[224:227], v[96:99], v[32:35]
	v_exp_f32_e32 v126, v126
	v_add_f32_e32 v221, v221, v125
	v_add_f32_e32 v221, v221, v126
	v_mfma_f32_16x16x32_bf16 v[36:39], v[224:227], v[104:107], v[36:39]
	v_exp_f32_e32 v127, v127
	v_mfma_f32_16x16x32_bf16 v[40:43], v[228:231], v[96:99], v[40:43]
	v_cvt_pk_bf16_f32 v123, v126, v127
	v_add_f32_e32 v221, v221, v127
	v_mfma_f32_16x16x32_bf16 v[44:47], v[228:231], v[104:107], v[44:47]
	v_mfma_f32_16x16x32_bf16 v[48:51], v[232:235], v[96:99], v[48:51]
	v_mfma_f32_16x16x32_bf16 v[52:55], v[232:235], v[104:107], v[52:55]
	v_mfma_f32_16x16x32_bf16 v[56:59], v[236:239], v[96:99], v[56:59]
	v_mfma_f32_16x16x32_bf16 v[60:63], v[236:239], v[104:107], v[60:63]
	ds_read_b128 v[224:227], v243 offset:8192
	ds_read_b128 v[228:231], v243 offset:10240
	ds_read_b128 v[232:235], v243 offset:12288
	ds_read_b128 v[236:239], v243 offset:14336
	s_waitcnt lgkmcnt(4)
	s_mov_b32 m0, s92
	v_mfma_f32_16x16x32_bf16 v[0:3], v[144:147], v[112:115], v[0:3]
	buffer_load_dwordx4 v205, s[28:31], s18 offen lds
	s_mov_b32 m0, s93
	v_mfma_f32_16x16x32_bf16 v[4:7], v[144:147], v[120:123], v[4:7]
	buffer_load_dwordx4 v205, s[28:31], s12 offen lds
	s_mov_b32 m0, s94
	v_mfma_f32_16x16x32_bf16 v[8:11], v[148:151], v[112:115], v[8:11]
	buffer_load_dwordx4 v206, s[36:39], s19 offen lds
	s_mov_b32 m0, s95
	v_mfma_f32_16x16x32_bf16 v[12:15], v[148:151], v[120:123], v[12:15]
	buffer_load_dwordx4 v206, s[36:39], s13 offen lds
	v_mfma_f32_16x16x32_bf16 v[16:19], v[152:155], v[112:115], v[16:19]
	v_mfma_f32_16x16x32_bf16 v[20:23], v[152:155], v[120:123], v[20:23]
	v_mfma_f32_16x16x32_bf16 v[24:27], v[156:159], v[112:115], v[24:27]
	v_mfma_f32_16x16x32_bf16 v[28:31], v[156:159], v[120:123], v[28:31]
	s_waitcnt vmcnt(4) lgkmcnt(0)
	s_barrier
	ds_read_b128 v[144:147], v217
	ds_read_b128 v[148:151], v217 offset:1024
	ds_read_b128 v[152:155], v217 offset:4096
	ds_read_b128 v[156:159], v217 offset:5120
	v_mfma_f32_16x16x32_bf16 v[32:35], v[224:227], v[112:115], v[32:35]
	v_mfma_f32_16x16x32_bf16 v[36:39], v[224:227], v[120:123], v[36:39]
	v_mfma_f32_16x16x32_bf16 v[40:43], v[228:231], v[112:115], v[40:43]
	v_mfma_f32_16x16x32_bf16 v[44:47], v[228:231], v[120:123], v[44:47]
	v_mfma_f32_16x16x32_bf16 v[48:51], v[232:235], v[112:115], v[48:51]
	v_mfma_f32_16x16x32_bf16 v[52:55], v[232:235], v[120:123], v[52:55]
	v_mfma_f32_16x16x32_bf16 v[56:59], v[236:239], v[112:115], v[56:59]
	v_mfma_f32_16x16x32_bf16 v[60:63], v[236:239], v[120:123], v[60:63]
	s_add_i32 s17, s14, 4
	s_min_u32 s17, s17, s15
	s_mul_i32 s18, s17, 0x30000
	s_lshl_b32 s19, s17, 7
	s_or_b32 s12, s18, 0x80
	s_add_i32 s13, s19, 0x200000
	ds_read_b128 v[224:227], v218
	ds_read_b128 v[228:231], v218 offset:1024
	ds_read_b128 v[232:235], v218 offset:4096
	ds_read_b128 v[236:239], v218 offset:5120
	s_waitcnt lgkmcnt(4)
	v_mfma_f32_16x16x32_bf16 v[96:99], v[144:147], v[128:131], 0
	v_exp_f32_e32 v64, v64
	v_exp_f32_e32 v65, v65
	v_add_f32_e32 v220, v220, v64
	v_add_f32_e32 v220, v220, v65
	v_mfma_f32_16x16x32_bf16 v[104:107], v[144:147], v[136:139], 0
	v_exp_f32_e32 v66, v66
	v_exp_f32_e32 v67, v67
	v_add_f32_e32 v220, v220, v66
	v_add_f32_e32 v220, v220, v67
	v_mfma_f32_16x16x32_bf16 v[100:103], v[148:151], v[128:131], 0
	v_exp_f32_e32 v68, v68
	v_exp_f32_e32 v69, v69
	v_cvt_pk_bf16_f32 v64, v64, v65
	v_add_f32_e32 v220, v220, v68
	v_mfma_f32_16x16x32_bf16 v[108:111], v[148:151], v[136:139], 0
	v_exp_f32_e32 v70, v70
	v_cvt_pk_bf16_f32 v65, v66, v67
	v_add_f32_e32 v220, v220, v69
	v_mfma_f32_16x16x32_bf16 v[112:115], v[152:155], v[128:131], 0
	v_exp_f32_e32 v71, v71
	v_cvt_pk_bf16_f32 v66, v68, v69
	v_cvt_pk_bf16_f32 v67, v70, v71
	v_mfma_f32_16x16x32_bf16 v[120:123], v[152:155], v[136:139], 0
	v_exp_f32_e32 v72, v72
	v_add_f32_e32 v220, v220, v70
	v_add_f32_e32 v221, v221, v72
	v_mfma_f32_16x16x32_bf16 v[116:119], v[156:159], v[128:131], 0
	v_exp_f32_e32 v73, v73
	v_add_f32_e32 v220, v220, v71
	v_add_f32_e32 v221, v221, v73
	v_mfma_f32_16x16x32_bf16 v[124:127], v[156:159], v[136:139], 0
	v_exp_f32_e32 v74, v74
	v_cvt_pk_bf16_f32 v72, v72, v73
	v_add_f32_e32 v221, v221, v74
	ds_read_b128 v[144:147], v242 offset:32768
	ds_read_b128 v[148:151], v242 offset:34816
	ds_read_b128 v[152:155], v242 offset:36864
	ds_read_b128 v[156:159], v242 offset:38912
	s_waitcnt lgkmcnt(4)
	v_mfma_f32_16x16x32_bf16 v[96:99], v[224:227], v[132:135], v[96:99]
	v_exp_f32_e32 v75, v75
	v_mfma_f32_16x16x32_bf16 v[104:107], v[224:227], v[140:143], v[104:107]
	v_exp_f32_e32 v76, v76
	v_add_f32_e32 v221, v221, v75
	v_cvt_pk_bf16_f32 v73, v74, v75
	v_mfma_f32_16x16x32_bf16 v[100:103], v[228:231], v[132:135], v[100:103]
	v_exp_f32_e32 v77, v77
	v_add_f32_e32 v221, v221, v76
	v_cvt_pk_bf16_f32 v74, v76, v77
	v_mfma_f32_16x16x32_bf16 v[108:111], v[228:231], v[140:143], v[108:111]
	v_exp_f32_e32 v78, v78
	v_add_f32_e32 v221, v221, v77
	v_add_f32_e32 v221, v221, v78
	v_mfma_f32_16x16x32_bf16 v[112:115], v[232:235], v[132:135], v[112:115]
	v_exp_f32_e32 v79, v79
	v_mfma_f32_16x16x32_bf16 v[120:123], v[232:235], v[140:143], v[120:123]
	v_cvt_pk_bf16_f32 v75, v78, v79
	v_exp_f32_e32 v80, v80
	v_add_f32_e32 v221, v221, v79
	v_mfma_f32_16x16x32_bf16 v[116:119], v[236:239], v[132:135], v[116:119]
	v_exp_f32_e32 v81, v81
	v_add_f32_e32 v220, v220, v80
	v_add_f32_e32 v220, v220, v81
	v_mfma_f32_16x16x32_bf16 v[124:127], v[236:239], v[140:143], v[124:127]
	v_exp_f32_e32 v82, v82
	v_cvt_pk_bf16_f32 v80, v80, v81
	v_add_f32_e32 v220, v220, v82
	ds_read_b128 v[224:227], v242 offset:40960
	ds_read_b128 v[228:231], v242 offset:43008
	ds_read_b128 v[232:235], v242 offset:45056
	ds_read_b128 v[236:239], v242 offset:47104
	s_waitcnt lgkmcnt(4)
	v_mfma_f32_16x16x32_bf16 v[0:3], v[144:147], v[64:67], v[0:3]
	v_exp_f32_e32 v83, v83
	v_exp_f32_e32 v84, v84
	v_add_f32_e32 v220, v220, v83
	v_cvt_pk_bf16_f32 v81, v82, v83
	v_mfma_f32_16x16x32_bf16 v[4:7], v[144:147], v[72:75], v[4:7]
	v_exp_f32_e32 v85, v85
	v_exp_f32_e32 v86, v86
	v_cvt_pk_bf16_f32 v82, v84, v85
	v_add_f32_e32 v220, v220, v84
	v_mfma_f32_16x16x32_bf16 v[8:11], v[148:151], v[64:67], v[8:11]
	v_exp_f32_e32 v87, v87
	v_exp_f32_e32 v88, v88
	v_cvt_pk_bf16_f32 v83, v86, v87
	v_add_f32_e32 v221, v221, v88
	v_mfma_f32_16x16x32_bf16 v[12:15], v[148:151], v[72:75], v[12:15]
	v_exp_f32_e32 v89, v89
	v_add_f32_e32 v220, v220, v85
	v_add_f32_e32 v221, v221, v89
	v_mfma_f32_16x16x32_bf16 v[16:19], v[152:155], v[64:67], v[16:19]
	v_exp_f32_e32 v90, v90
	v_cvt_pk_bf16_f32 v88, v88, v89
	v_add_f32_e32 v221, v221, v90
	v_mfma_f32_16x16x32_bf16 v[20:23], v[152:155], v[72:75], v[20:23]
	v_exp_f32_e32 v91, v91
	v_add_f32_e32 v220, v220, v86
	v_add_f32_e32 v221, v221, v91
	v_mfma_f32_16x16x32_bf16 v[24:27], v[156:159], v[64:67], v[24:27]
	v_exp_f32_e32 v92, v92
	v_cvt_pk_bf16_f32 v89, v90, v91
	v_add_f32_e32 v220, v220, v87
	v_mfma_f32_16x16x32_bf16 v[28:31], v[156:159], v[72:75], v[28:31]
	v_exp_f32_e32 v93, v93
	v_add_f32_e32 v221, v221, v92
	v_cvt_pk_bf16_f32 v90, v92, v93
	ds_read_b128 v[144:147], v243 offset:32768
	ds_read_b128 v[148:151], v243 offset:34816
	ds_read_b128 v[152:155], v243 offset:36864
	ds_read_b128 v[156:159], v243 offset:38912
	s_waitcnt lgkmcnt(4)
	v_mfma_f32_16x16x32_bf16 v[32:35], v[224:227], v[64:67], v[32:35]
	v_exp_f32_e32 v94, v94
	v_add_f32_e32 v221, v221, v93
	v_add_f32_e32 v221, v221, v94
	v_mfma_f32_16x16x32_bf16 v[36:39], v[224:227], v[72:75], v[36:39]
	v_exp_f32_e32 v95, v95
	v_mfma_f32_16x16x32_bf16 v[40:43], v[228:231], v[64:67], v[40:43]
	v_cvt_pk_bf16_f32 v91, v94, v95
	v_add_f32_e32 v221, v221, v95
	v_mfma_f32_16x16x32_bf16 v[44:47], v[228:231], v[72:75], v[44:47]
	v_mfma_f32_16x16x32_bf16 v[48:51], v[232:235], v[64:67], v[48:51]
	v_mfma_f32_16x16x32_bf16 v[52:55], v[232:235], v[72:75], v[52:55]
	v_mfma_f32_16x16x32_bf16 v[56:59], v[236:239], v[64:67], v[56:59]
	v_mfma_f32_16x16x32_bf16 v[60:63], v[236:239], v[72:75], v[60:63]
	ds_read_b128 v[224:227], v243 offset:40960
	ds_read_b128 v[228:231], v243 offset:43008
	ds_read_b128 v[232:235], v243 offset:45056
	ds_read_b128 v[236:239], v243 offset:47104
	s_waitcnt lgkmcnt(4)
	s_mov_b32 m0, s72
	v_mfma_f32_16x16x32_bf16 v[0:3], v[144:147], v[80:83], v[0:3]
	buffer_load_dwordx4 v205, s[28:31], s18 offen lds
	s_mov_b32 m0, s73
	v_mfma_f32_16x16x32_bf16 v[4:7], v[144:147], v[88:91], v[4:7]
	buffer_load_dwordx4 v205, s[28:31], s12 offen lds
	s_mov_b32 m0, s6
	v_mfma_f32_16x16x32_bf16 v[8:11], v[148:151], v[80:83], v[8:11]
	buffer_load_dwordx4 v206, s[36:39], s19 offen lds
	s_mov_b32 m0, s7
	v_mfma_f32_16x16x32_bf16 v[12:15], v[148:151], v[88:91], v[12:15]
	buffer_load_dwordx4 v206, s[36:39], s13 offen lds
	v_mfma_f32_16x16x32_bf16 v[16:19], v[152:155], v[80:83], v[16:19]
	v_mfma_f32_16x16x32_bf16 v[20:23], v[152:155], v[88:91], v[20:23]
	v_mfma_f32_16x16x32_bf16 v[24:27], v[156:159], v[80:83], v[24:27]
	v_mfma_f32_16x16x32_bf16 v[28:31], v[156:159], v[88:91], v[28:31]
	s_waitcnt vmcnt(4) lgkmcnt(0)
	s_barrier
	ds_read_b128 v[144:147], v217 offset:32768
	ds_read_b128 v[148:151], v217 offset:33792
	ds_read_b128 v[152:155], v217 offset:36864
	ds_read_b128 v[156:159], v217 offset:37888
	v_mfma_f32_16x16x32_bf16 v[32:35], v[224:227], v[80:83], v[32:35]
	v_mfma_f32_16x16x32_bf16 v[36:39], v[224:227], v[88:91], v[36:39]
	v_mfma_f32_16x16x32_bf16 v[40:43], v[228:231], v[80:83], v[40:43]
	v_mfma_f32_16x16x32_bf16 v[44:47], v[228:231], v[88:91], v[44:47]
	v_mfma_f32_16x16x32_bf16 v[48:51], v[232:235], v[80:83], v[48:51]
	v_mfma_f32_16x16x32_bf16 v[52:55], v[232:235], v[88:91], v[52:55]
	v_mfma_f32_16x16x32_bf16 v[56:59], v[236:239], v[80:83], v[56:59]
	v_mfma_f32_16x16x32_bf16 v[60:63], v[236:239], v[88:91], v[60:63]
	s_add_i32 s17, s14, 5
	s_min_u32 s17, s17, s15
	s_mul_i32 s18, s17, 0x30000
	s_lshl_b32 s19, s17, 7
	s_or_b32 s12, s18, 0x80
	s_add_i32 s13, s19, 0x200000
	s_add_i32 s17, s14, 2
	s_lshl_b32 s17, s17, 6
	v_subrev_u32_e32 v248, s17, v246
	v_subrev_u32_e32 v249, s17, v247
	v_cmp_gt_i32_e64 vcc, 0, v248
	v_cmp_gt_i32_e64 s[98:99], 1, v248
	v_cmp_gt_i32_e64 s[100:101], 2, v248
	v_cndmask_b32_e64 v96, v96, v197, vcc
	v_cmp_gt_i32_e64 vcc, 3, v248
	v_cndmask_b32_e64 v97, v97, v197, s[98:99]
	v_cmp_gt_i32_e64 s[98:99], 8, v248
	v_cndmask_b32_e64 v98, v98, v197, s[100:101]
	v_cmp_gt_i32_e64 s[100:101], 9, v248
	v_cndmask_b32_e64 v99, v99, v197, vcc
	v_cmp_gt_i32_e64 vcc, 10, v248
	v_cndmask_b32_e64 v100, v100, v197, s[98:99]
	v_cmp_gt_i32_e64 s[98:99], 11, v248
	v_cndmask_b32_e64 v101, v101, v197, s[100:101]
	v_cmp_gt_i32_e64 s[100:101], 0, v249
	v_cndmask_b32_e64 v102, v102, v197, vcc
	v_cmp_gt_i32_e64 vcc, 1, v249
	v_cndmask_b32_e64 v103, v103, v197, s[98:99]
	v_cmp_gt_i32_e64 s[98:99], 2, v249
	v_cndmask_b32_e64 v104, v104, v197, s[100:101]
	v_cmp_gt_i32_e64 s[100:101], 3, v249
	v_cndmask_b32_e64 v105, v105, v197, vcc
	v_cmp_gt_i32_e64 vcc, 8, v249
	v_cndmask_b32_e64 v106, v106, v197, s[98:99]
	v_cmp_gt_i32_e64 s[98:99], 9, v249
	v_cndmask_b32_e64 v107, v107, v197, s[100:101]
	v_cmp_gt_i32_e64 s[100:101], 10, v249
	v_cndmask_b32_e64 v108, v108, v197, vcc
	v_cmp_gt_i32_e64 vcc, 11, v249
	v_cndmask_b32_e64 v109, v109, v197, s[98:99]
	v_cmp_gt_i32_e64 s[98:99], 32, v248
	v_cndmask_b32_e64 v110, v110, v197, s[100:101]
	v_cmp_gt_i32_e64 s[100:101], 33, v248
	v_cndmask_b32_e64 v111, v111, v197, vcc
	v_cmp_gt_i32_e64 vcc, 34, v248
	v_cndmask_b32_e64 v112, v112, v197, s[98:99]
	v_cmp_gt_i32_e64 s[98:99], 35, v248
	v_cndmask_b32_e64 v113, v113, v197, s[100:101]
	v_cmp_gt_i32_e64 s[100:101], 40, v248
	v_cndmask_b32_e64 v114, v114, v197, vcc
	v_cmp_gt_i32_e64 vcc, 41, v248
	v_cndmask_b32_e64 v115, v115, v197, s[98:99]
	v_cmp_gt_i32_e64 s[98:99], 42, v248
	v_cndmask_b32_e64 v116, v116, v197, s[100:101]
	v_cmp_gt_i32_e64 s[100:101], 43, v248
	v_cndmask_b32_e64 v117, v117, v197, vcc
	v_cmp_gt_i32_e64 vcc, 32, v249
	v_cndmask_b32_e64 v118, v118, v197, s[98:99]
	v_cmp_gt_i32_e64 s[98:99], 33, v249
	v_cndmask_b32_e64 v119, v119, v197, s[100:101]
	v_cmp_gt_i32_e64 s[100:101], 34, v249
	v_cndmask_b32_e64 v120, v120, v197, vcc
	v_cmp_gt_i32_e64 vcc, 35, v249
	v_cndmask_b32_e64 v121, v121, v197, s[98:99]
	v_cmp_gt_i32_e64 s[98:99], 40, v249
	v_cndmask_b32_e64 v122, v122, v197, s[100:101]
	v_cmp_gt_i32_e64 s[100:101], 41, v249
	v_cndmask_b32_e64 v123, v123, v197, vcc
	v_cmp_gt_i32_e64 vcc, 42, v249
	v_cndmask_b32_e64 v124, v124, v197, s[98:99]
	v_cmp_gt_i32_e64 s[98:99], 43, v249
	v_cndmask_b32_e64 v125, v125, v197, s[100:101]
	s_nop 0
	v_cndmask_b32_e64 v126, v126, v197, vcc
	s_nop 0
	v_cndmask_b32_e64 v127, v127, v197, s[98:99]
	s_nop 0
	ds_read_b128 v[224:227], v218 offset:32768
	ds_read_b128 v[228:231], v218 offset:33792
	ds_read_b128 v[232:235], v218 offset:36864
	ds_read_b128 v[236:239], v218 offset:37888
	s_waitcnt lgkmcnt(4)
	v_mfma_f32_16x16x32_bf16 v[64:67], v[144:147], v[128:131], 0
	v_exp_f32_e32 v96, v96
	v_exp_f32_e32 v97, v97
	v_add_f32_e32 v220, v220, v96
	v_add_f32_e32 v220, v220, v97
	v_cvt_pk_bf16_f32 v96, v96, v97
	v_mfma_f32_16x16x32_bf16 v[72:75], v[144:147], v[136:139], 0
	v_exp_f32_e32 v98, v98
	v_exp_f32_e32 v99, v99
	v_add_f32_e32 v220, v220, v98
	v_add_f32_e32 v220, v220, v99
	v_cvt_pk_bf16_f32 v97, v98, v99
	v_mfma_f32_16x16x32_bf16 v[68:71], v[148:151], v[128:131], 0
	v_exp_f32_e32 v100, v100
	v_exp_f32_e32 v101, v101
	v_add_f32_e32 v220, v220, v100
	v_cvt_pk_bf16_f32 v98, v100, v101
	v_add_f32_e32 v220, v220, v101
	v_mfma_f32_16x16x32_bf16 v[76:79], v[148:151], v[136:139], 0
	v_exp_f32_e32 v102, v102
	v_exp_f32_e32 v103, v103
	v_add_f32_e32 v220, v220, v102
	v_cvt_pk_bf16_f32 v99, v102, v103
	v_add_f32_e32 v220, v220, v103
	v_mfma_f32_16x16x32_bf16 v[80:83], v[152:155], v[128:131], 0
	v_exp_f32_e32 v104, v104
	v_exp_f32_e32 v105, v105
	v_add_f32_e32 v221, v221, v104
	v_add_f32_e32 v221, v221, v105
	v_cvt_pk_bf16_f32 v104, v104, v105
	v_mfma_f32_16x16x32_bf16 v[88:91], v[152:155], v[136:139], 0
	v_exp_f32_e32 v106, v106
	v_exp_f32_e32 v107, v107
	v_add_f32_e32 v221, v221, v106
	v_add_f32_e32 v221, v221, v107
	v_cvt_pk_bf16_f32 v105, v106, v107
	v_mfma_f32_16x16x32_bf16 v[84:87], v[156:159], v[128:131], 0
	v_exp_f32_e32 v108, v108
	v_exp_f32_e32 v109, v109
	v_add_f32_e32 v221, v221, v108
	v_cvt_pk_bf16_f32 v106, v108, v109
	v_add_f32_e32 v221, v221, v109
	v_mfma_f32_16x16x32_bf16 v[92:95], v[156:159], v[136:139], 0
	v_exp_f32_e32 v110, v110
	v_exp_f32_e32 v111, v111
	v_add_f32_e32 v221, v221, v110
	v_cvt_pk_bf16_f32 v107, v110, v111
	v_add_f32_e32 v221, v221, v111
	ds_read_b128 v[144:147], v244
	ds_read_b128 v[148:151], v244 offset:2048
	ds_read_b128 v[152:155], v244 offset:4096
	ds_read_b128 v[156:159], v244 offset:6144
	s_waitcnt lgkmcnt(4)
	v_mfma_f32_16x16x32_bf16 v[64:67], v[224:227], v[132:135], v[64:67]
	v_exp_f32_e32 v112, v112
	v_exp_f32_e32 v113, v113
	v_add_f32_e32 v220, v220, v112
	v_add_f32_e32 v220, v220, v113
	v_cvt_pk_bf16_f32 v112, v112, v113
	v_mfma_f32_16x16x32_bf16 v[72:75], v[224:227], v[140:143], v[72:75]
	v_exp_f32_e32 v114, v114
	v_exp_f32_e32 v115, v115
	v_add_f32_e32 v220, v220, v114
	v_add_f32_e32 v220, v220, v115
	v_cvt_pk_bf16_f32 v113, v114, v115
	v_mfma_f32_16x16x32_bf16 v[68:71], v[228:231], v[132:135], v[68:71]
	v_exp_f32_e32 v116, v116
	v_exp_f32_e32 v117, v117
	v_add_f32_e32 v220, v220, v116
	v_cvt_pk_bf16_f32 v114, v116, v117
	v_add_f32_e32 v220, v220, v117
	v_mfma_f32_16x16x32_bf16 v[76:79], v[228:231], v[140:143], v[76:79]
	v_exp_f32_e32 v118, v118
	v_exp_f32_e32 v119, v119
	v_add_f32_e32 v220, v220, v118
	v_cvt_pk_bf16_f32 v115, v118, v119
	v_add_f32_e32 v220, v220, v119
	v_mfma_f32_16x16x32_bf16 v[80:83], v[232:235], v[132:135], v[80:83]
	v_exp_f32_e32 v120, v120
	v_exp_f32_e32 v121, v121
	v_add_f32_e32 v221, v221, v120
	v_add_f32_e32 v221, v221, v121
	v_cvt_pk_bf16_f32 v120, v120, v121
	v_mfma_f32_16x16x32_bf16 v[88:91], v[232:235], v[140:143], v[88:91]
	v_exp_f32_e32 v122, v122
	v_exp_f32_e32 v123, v123
	v_add_f32_e32 v221, v221, v122
	v_add_f32_e32 v221, v221, v123
	v_cvt_pk_bf16_f32 v121, v122, v123
	v_mfma_f32_16x16x32_bf16 v[84:87], v[236:239], v[132:135], v[84:87]
	v_exp_f32_e32 v124, v124
	v_exp_f32_e32 v125, v125
	v_add_f32_e32 v221, v221, v124
	v_cvt_pk_bf16_f32 v122, v124, v125
	v_add_f32_e32 v221, v221, v125
	v_mfma_f32_16x16x32_bf16 v[92:95], v[236:239], v[140:143], v[92:95]
	v_exp_f32_e32 v126, v126
	v_exp_f32_e32 v127, v127
	v_add_f32_e32 v221, v221, v126
	v_cvt_pk_bf16_f32 v123, v126, v127
	v_add_f32_e32 v221, v221, v127
	ds_read_b128 v[224:227], v244 offset:8192
	ds_read_b128 v[228:231], v244 offset:10240
	ds_read_b128 v[232:235], v244 offset:12288
	ds_read_b128 v[236:239], v244 offset:14336
	s_waitcnt lgkmcnt(4)
	v_mfma_f32_16x16x32_bf16 v[0:3], v[144:147], v[96:99], v[0:3]
	v_mfma_f32_16x16x32_bf16 v[4:7], v[144:147], v[104:107], v[4:7]
	v_mfma_f32_16x16x32_bf16 v[8:11], v[148:151], v[96:99], v[8:11]
	v_mfma_f32_16x16x32_bf16 v[12:15], v[148:151], v[104:107], v[12:15]
	v_mfma_f32_16x16x32_bf16 v[16:19], v[152:155], v[96:99], v[16:19]
	v_mfma_f32_16x16x32_bf16 v[20:23], v[152:155], v[104:107], v[20:23]
	v_mfma_f32_16x16x32_bf16 v[24:27], v[156:159], v[96:99], v[24:27]
	v_mfma_f32_16x16x32_bf16 v[28:31], v[156:159], v[104:107], v[28:31]
	ds_read_b128 v[144:147], v245
	ds_read_b128 v[148:151], v245 offset:2048
	ds_read_b128 v[152:155], v245 offset:4096
	ds_read_b128 v[156:159], v245 offset:6144
	s_waitcnt lgkmcnt(4)
	v_mfma_f32_16x16x32_bf16 v[32:35], v[224:227], v[96:99], v[32:35]
	v_mfma_f32_16x16x32_bf16 v[36:39], v[224:227], v[104:107], v[36:39]
	v_mfma_f32_16x16x32_bf16 v[40:43], v[228:231], v[96:99], v[40:43]
	v_mfma_f32_16x16x32_bf16 v[44:47], v[228:231], v[104:107], v[44:47]
	v_mfma_f32_16x16x32_bf16 v[48:51], v[232:235], v[96:99], v[48:51]
	v_mfma_f32_16x16x32_bf16 v[52:55], v[232:235], v[104:107], v[52:55]
	v_mfma_f32_16x16x32_bf16 v[56:59], v[236:239], v[96:99], v[56:59]
	v_mfma_f32_16x16x32_bf16 v[60:63], v[236:239], v[104:107], v[60:63]
	ds_read_b128 v[224:227], v245 offset:8192
	ds_read_b128 v[228:231], v245 offset:10240
	ds_read_b128 v[232:235], v245 offset:12288
	ds_read_b128 v[236:239], v245 offset:14336
	s_waitcnt lgkmcnt(4)
	s_mov_b32 m0, s8
	v_mfma_f32_16x16x32_bf16 v[0:3], v[144:147], v[112:115], v[0:3]
	buffer_load_dwordx4 v205, s[28:31], s18 offen lds
	s_mov_b32 m0, s9
	v_mfma_f32_16x16x32_bf16 v[4:7], v[144:147], v[120:123], v[4:7]
	buffer_load_dwordx4 v205, s[28:31], s12 offen lds
	s_mov_b32 m0, s58
	v_mfma_f32_16x16x32_bf16 v[8:11], v[148:151], v[112:115], v[8:11]
	buffer_load_dwordx4 v206, s[36:39], s19 offen lds
	s_mov_b32 m0, s79
	v_mfma_f32_16x16x32_bf16 v[12:15], v[148:151], v[120:123], v[12:15]
	buffer_load_dwordx4 v206, s[36:39], s13 offen lds
	v_mfma_f32_16x16x32_bf16 v[16:19], v[152:155], v[112:115], v[16:19]
	v_mfma_f32_16x16x32_bf16 v[20:23], v[152:155], v[120:123], v[20:23]
	v_mfma_f32_16x16x32_bf16 v[24:27], v[156:159], v[112:115], v[24:27]
	v_mfma_f32_16x16x32_bf16 v[28:31], v[156:159], v[120:123], v[28:31]
	s_waitcnt vmcnt(4) lgkmcnt(0)
	s_barrier
	ds_read_b128 v[144:147], v240
	ds_read_b128 v[148:151], v240 offset:1024
	ds_read_b128 v[152:155], v240 offset:4096
	ds_read_b128 v[156:159], v240 offset:5120
	v_mfma_f32_16x16x32_bf16 v[32:35], v[224:227], v[112:115], v[32:35]
	v_mfma_f32_16x16x32_bf16 v[36:39], v[224:227], v[120:123], v[36:39]
	v_mfma_f32_16x16x32_bf16 v[40:43], v[228:231], v[112:115], v[40:43]
	v_mfma_f32_16x16x32_bf16 v[44:47], v[228:231], v[120:123], v[44:47]
	v_mfma_f32_16x16x32_bf16 v[48:51], v[232:235], v[112:115], v[48:51]
	v_mfma_f32_16x16x32_bf16 v[52:55], v[232:235], v[120:123], v[52:55]
	v_mfma_f32_16x16x32_bf16 v[56:59], v[236:239], v[112:115], v[56:59]
	v_mfma_f32_16x16x32_bf16 v[60:63], v[236:239], v[120:123], v[60:63]
	s_add_i32 s17, s14, 6
	s_min_u32 s17, s17, s15
	s_mul_i32 s18, s17, 0x30000
	s_lshl_b32 s19, s17, 7
	s_or_b32 s12, s18, 0x80
	s_add_i32 s13, s19, 0x200000
	s_add_i32 s17, s14, 3
	s_lshl_b32 s17, s17, 6
	v_subrev_u32_e32 v248, s17, v246
	v_subrev_u32_e32 v249, s17, v247
	v_cmp_gt_i32_e64 vcc, 0, v248
	v_cmp_gt_i32_e64 s[98:99], 1, v248
	v_cmp_gt_i32_e64 s[100:101], 2, v248
	v_cndmask_b32_e64 v64, v64, v197, vcc
	v_cmp_gt_i32_e64 vcc, 3, v248
	v_cndmask_b32_e64 v65, v65, v197, s[98:99]
	v_cmp_gt_i32_e64 s[98:99], 8, v248
	v_cndmask_b32_e64 v66, v66, v197, s[100:101]
	v_cmp_gt_i32_e64 s[100:101], 9, v248
	v_cndmask_b32_e64 v67, v67, v197, vcc
	v_cmp_gt_i32_e64 vcc, 10, v248
	v_cndmask_b32_e64 v68, v68, v197, s[98:99]
	v_cmp_gt_i32_e64 s[98:99], 11, v248
	v_cndmask_b32_e64 v69, v69, v197, s[100:101]
	v_cmp_gt_i32_e64 s[100:101], 0, v249
	v_cndmask_b32_e64 v70, v70, v197, vcc
	v_cmp_gt_i32_e64 vcc, 1, v249
	v_cndmask_b32_e64 v71, v71, v197, s[98:99]
	v_cmp_gt_i32_e64 s[98:99], 2, v249
	v_cndmask_b32_e64 v72, v72, v197, s[100:101]
	v_cmp_gt_i32_e64 s[100:101], 3, v249
	v_cndmask_b32_e64 v73, v73, v197, vcc
	v_cmp_gt_i32_e64 vcc, 8, v249
	v_cndmask_b32_e64 v74, v74, v197, s[98:99]
	v_cmp_gt_i32_e64 s[98:99], 9, v249
	v_cndmask_b32_e64 v75, v75, v197, s[100:101]
	v_cmp_gt_i32_e64 s[100:101], 10, v249
	v_cndmask_b32_e64 v76, v76, v197, vcc
	v_cmp_gt_i32_e64 vcc, 11, v249
	v_cndmask_b32_e64 v77, v77, v197, s[98:99]
	v_cmp_gt_i32_e64 s[98:99], 32, v248
	v_cndmask_b32_e64 v78, v78, v197, s[100:101]
	v_cmp_gt_i32_e64 s[100:101], 33, v248
	v_cndmask_b32_e64 v79, v79, v197, vcc
	v_cmp_gt_i32_e64 vcc, 34, v248
	v_cndmask_b32_e64 v80, v80, v197, s[98:99]
	v_cmp_gt_i32_e64 s[98:99], 35, v248
	v_cndmask_b32_e64 v81, v81, v197, s[100:101]
	v_cmp_gt_i32_e64 s[100:101], 40, v248
	v_cndmask_b32_e64 v82, v82, v197, vcc
	v_cmp_gt_i32_e64 vcc, 41, v248
	v_cndmask_b32_e64 v83, v83, v197, s[98:99]
	v_cmp_gt_i32_e64 s[98:99], 42, v248
	v_cndmask_b32_e64 v84, v84, v197, s[100:101]
	v_cmp_gt_i32_e64 s[100:101], 43, v248
	v_cndmask_b32_e64 v85, v85, v197, vcc
	v_cmp_gt_i32_e64 vcc, 32, v249
	v_cndmask_b32_e64 v86, v86, v197, s[98:99]
	v_cmp_gt_i32_e64 s[98:99], 33, v249
	v_cndmask_b32_e64 v87, v87, v197, s[100:101]
	v_cmp_gt_i32_e64 s[100:101], 34, v249
	v_cndmask_b32_e64 v88, v88, v197, vcc
	v_cmp_gt_i32_e64 vcc, 35, v249
	v_cndmask_b32_e64 v89, v89, v197, s[98:99]
	v_cmp_gt_i32_e64 s[98:99], 40, v249
	v_cndmask_b32_e64 v90, v90, v197, s[100:101]
	v_cmp_gt_i32_e64 s[100:101], 41, v249
	v_cndmask_b32_e64 v91, v91, v197, vcc
	v_cmp_gt_i32_e64 vcc, 42, v249
	v_cndmask_b32_e64 v92, v92, v197, s[98:99]
	v_cmp_gt_i32_e64 s[98:99], 43, v249
	v_cndmask_b32_e64 v93, v93, v197, s[100:101]
	s_nop 0
	v_cndmask_b32_e64 v94, v94, v197, vcc
	s_nop 0
	v_cndmask_b32_e64 v95, v95, v197, s[98:99]
	s_nop 0
	ds_read_b128 v[224:227], v241
	ds_read_b128 v[228:231], v241 offset:1024
	ds_read_b128 v[232:235], v241 offset:4096
	ds_read_b128 v[236:239], v241 offset:5120
	s_waitcnt lgkmcnt(4)
	v_mfma_f32_16x16x32_bf16 v[96:99], v[144:147], v[128:131], 0
	v_exp_f32_e32 v64, v64
	v_exp_f32_e32 v65, v65
	v_add_f32_e32 v220, v220, v64
	v_add_f32_e32 v220, v220, v65
	v_cvt_pk_bf16_f32 v64, v64, v65
	v_mfma_f32_16x16x32_bf16 v[104:107], v[144:147], v[136:139], 0
	v_exp_f32_e32 v66, v66
	v_exp_f32_e32 v67, v67
	v_add_f32_e32 v220, v220, v66
	v_add_f32_e32 v220, v220, v67
	v_cvt_pk_bf16_f32 v65, v66, v67
	v_mfma_f32_16x16x32_bf16 v[100:103], v[148:151], v[128:131], 0
	v_exp_f32_e32 v68, v68
	v_exp_f32_e32 v69, v69
	v_add_f32_e32 v220, v220, v68
	v_cvt_pk_bf16_f32 v66, v68, v69
	v_add_f32_e32 v220, v220, v69
	v_mfma_f32_16x16x32_bf16 v[108:111], v[148:151], v[136:139], 0
	v_exp_f32_e32 v70, v70
	v_exp_f32_e32 v71, v71
	v_add_f32_e32 v220, v220, v70
	v_cvt_pk_bf16_f32 v67, v70, v71
	v_add_f32_e32 v220, v220, v71
	v_mfma_f32_16x16x32_bf16 v[112:115], v[152:155], v[128:131], 0
	v_exp_f32_e32 v72, v72
	v_exp_f32_e32 v73, v73
	v_add_f32_e32 v221, v221, v72
	v_add_f32_e32 v221, v221, v73
	v_cvt_pk_bf16_f32 v72, v72, v73
	v_mfma_f32_16x16x32_bf16 v[120:123], v[152:155], v[136:139], 0
	v_exp_f32_e32 v74, v74
	v_exp_f32_e32 v75, v75
	v_add_f32_e32 v221, v221, v74
	v_add_f32_e32 v221, v221, v75
	v_cvt_pk_bf16_f32 v73, v74, v75
	v_mfma_f32_16x16x32_bf16 v[116:119], v[156:159], v[128:131], 0
	v_exp_f32_e32 v76, v76
	v_exp_f32_e32 v77, v77
	v_add_f32_e32 v221, v221, v76
	v_cvt_pk_bf16_f32 v74, v76, v77
	v_add_f32_e32 v221, v221, v77
	v_mfma_f32_16x16x32_bf16 v[124:127], v[156:159], v[136:139], 0
	v_exp_f32_e32 v78, v78
	v_exp_f32_e32 v79, v79
	v_add_f32_e32 v221, v221, v78
	v_cvt_pk_bf16_f32 v75, v78, v79
	v_add_f32_e32 v221, v221, v79
	ds_read_b128 v[144:147], v244 offset:32768
	ds_read_b128 v[148:151], v244 offset:34816
	ds_read_b128 v[152:155], v244 offset:36864
	ds_read_b128 v[156:159], v244 offset:38912
	s_waitcnt lgkmcnt(4)
	v_mfma_f32_16x16x32_bf16 v[96:99], v[224:227], v[132:135], v[96:99]
	v_exp_f32_e32 v80, v80
	v_exp_f32_e32 v81, v81
	v_add_f32_e32 v220, v220, v80
	v_add_f32_e32 v220, v220, v81
	v_cvt_pk_bf16_f32 v80, v80, v81
	v_mfma_f32_16x16x32_bf16 v[104:107], v[224:227], v[140:143], v[104:107]
	v_exp_f32_e32 v82, v82
	v_exp_f32_e32 v83, v83
	v_add_f32_e32 v220, v220, v82
	v_add_f32_e32 v220, v220, v83
	v_cvt_pk_bf16_f32 v81, v82, v83
	v_mfma_f32_16x16x32_bf16 v[100:103], v[228:231], v[132:135], v[100:103]
	v_exp_f32_e32 v84, v84
	v_exp_f32_e32 v85, v85
	v_add_f32_e32 v220, v220, v84
	v_cvt_pk_bf16_f32 v82, v84, v85
	v_add_f32_e32 v220, v220, v85
	v_mfma_f32_16x16x32_bf16 v[108:111], v[228:231], v[140:143], v[108:111]
	v_exp_f32_e32 v86, v86
	v_exp_f32_e32 v87, v87
	v_add_f32_e32 v220, v220, v86
	v_cvt_pk_bf16_f32 v83, v86, v87
	v_add_f32_e32 v220, v220, v87
	v_mfma_f32_16x16x32_bf16 v[112:115], v[232:235], v[132:135], v[112:115]
	v_exp_f32_e32 v88, v88
	v_exp_f32_e32 v89, v89
	v_add_f32_e32 v221, v221, v88
	v_add_f32_e32 v221, v221, v89
	v_cvt_pk_bf16_f32 v88, v88, v89
	v_mfma_f32_16x16x32_bf16 v[120:123], v[232:235], v[140:143], v[120:123]
	v_exp_f32_e32 v90, v90
	v_exp_f32_e32 v91, v91
	v_add_f32_e32 v221, v221, v90
	v_add_f32_e32 v221, v221, v91
	v_cvt_pk_bf16_f32 v89, v90, v91
	v_mfma_f32_16x16x32_bf16 v[116:119], v[236:239], v[132:135], v[116:119]
	v_exp_f32_e32 v92, v92
	v_exp_f32_e32 v93, v93
	v_add_f32_e32 v221, v221, v92
	v_cvt_pk_bf16_f32 v90, v92, v93
	v_add_f32_e32 v221, v221, v93
	v_mfma_f32_16x16x32_bf16 v[124:127], v[236:239], v[140:143], v[124:127]
	v_exp_f32_e32 v94, v94
	v_exp_f32_e32 v95, v95
	v_add_f32_e32 v221, v221, v94
	v_cvt_pk_bf16_f32 v91, v94, v95
	v_add_f32_e32 v221, v221, v95
	ds_read_b128 v[224:227], v244 offset:40960
	ds_read_b128 v[228:231], v244 offset:43008
	ds_read_b128 v[232:235], v244 offset:45056
	ds_read_b128 v[236:239], v244 offset:47104
	s_waitcnt lgkmcnt(4)
	v_mfma_f32_16x16x32_bf16 v[0:3], v[144:147], v[64:67], v[0:3]
	v_mfma_f32_16x16x32_bf16 v[4:7], v[144:147], v[72:75], v[4:7]
	v_mfma_f32_16x16x32_bf16 v[8:11], v[148:151], v[64:67], v[8:11]
	v_mfma_f32_16x16x32_bf16 v[12:15], v[148:151], v[72:75], v[12:15]
	v_mfma_f32_16x16x32_bf16 v[16:19], v[152:155], v[64:67], v[16:19]
	v_mfma_f32_16x16x32_bf16 v[20:23], v[152:155], v[72:75], v[20:23]
	v_mfma_f32_16x16x32_bf16 v[24:27], v[156:159], v[64:67], v[24:27]
	v_mfma_f32_16x16x32_bf16 v[28:31], v[156:159], v[72:75], v[28:31]
	ds_read_b128 v[144:147], v245 offset:32768
	ds_read_b128 v[148:151], v245 offset:34816
	ds_read_b128 v[152:155], v245 offset:36864
	ds_read_b128 v[156:159], v245 offset:38912
	s_waitcnt lgkmcnt(4)
	v_mfma_f32_16x16x32_bf16 v[32:35], v[224:227], v[64:67], v[32:35]
	v_mfma_f32_16x16x32_bf16 v[36:39], v[224:227], v[72:75], v[36:39]
	v_mfma_f32_16x16x32_bf16 v[40:43], v[228:231], v[64:67], v[40:43]
	v_mfma_f32_16x16x32_bf16 v[44:47], v[228:231], v[72:75], v[44:47]
	v_mfma_f32_16x16x32_bf16 v[48:51], v[232:235], v[64:67], v[48:51]
	v_mfma_f32_16x16x32_bf16 v[52:55], v[232:235], v[72:75], v[52:55]
	v_mfma_f32_16x16x32_bf16 v[56:59], v[236:239], v[64:67], v[56:59]
	v_mfma_f32_16x16x32_bf16 v[60:63], v[236:239], v[72:75], v[60:63]
	ds_read_b128 v[224:227], v245 offset:40960
	ds_read_b128 v[228:231], v245 offset:43008
	ds_read_b128 v[232:235], v245 offset:45056
	ds_read_b128 v[236:239], v245 offset:47104
	s_waitcnt lgkmcnt(4)
	s_mov_b32 m0, s52
	v_mfma_f32_16x16x32_bf16 v[0:3], v[144:147], v[80:83], v[0:3]
	buffer_load_dwordx4 v205, s[28:31], s18 offen lds
	s_mov_b32 m0, s53
	v_mfma_f32_16x16x32_bf16 v[4:7], v[144:147], v[88:91], v[4:7]
	buffer_load_dwordx4 v205, s[28:31], s12 offen lds
	s_mov_b32 m0, s90
	v_mfma_f32_16x16x32_bf16 v[8:11], v[148:151], v[80:83], v[8:11]
	buffer_load_dwordx4 v206, s[36:39], s19 offen lds
	s_mov_b32 m0, s91
	v_mfma_f32_16x16x32_bf16 v[12:15], v[148:151], v[88:91], v[12:15]
	buffer_load_dwordx4 v206, s[36:39], s13 offen lds
	v_mfma_f32_16x16x32_bf16 v[16:19], v[152:155], v[80:83], v[16:19]
	v_mfma_f32_16x16x32_bf16 v[20:23], v[152:155], v[88:91], v[20:23]
	v_mfma_f32_16x16x32_bf16 v[24:27], v[156:159], v[80:83], v[24:27]
	v_mfma_f32_16x16x32_bf16 v[28:31], v[156:159], v[88:91], v[28:31]
	s_waitcnt vmcnt(4) lgkmcnt(0)
	s_barrier
	ds_read_b128 v[144:147], v240 offset:32768
	ds_read_b128 v[148:151], v240 offset:33792
	ds_read_b128 v[152:155], v240 offset:36864
	ds_read_b128 v[156:159], v240 offset:37888
	v_mfma_f32_16x16x32_bf16 v[32:35], v[224:227], v[80:83], v[32:35]
	v_mfma_f32_16x16x32_bf16 v[36:39], v[224:227], v[88:91], v[36:39]
	v_mfma_f32_16x16x32_bf16 v[40:43], v[228:231], v[80:83], v[40:43]
	v_mfma_f32_16x16x32_bf16 v[44:47], v[228:231], v[88:91], v[44:47]
	v_mfma_f32_16x16x32_bf16 v[48:51], v[232:235], v[80:83], v[48:51]
	v_mfma_f32_16x16x32_bf16 v[52:55], v[232:235], v[88:91], v[52:55]
	v_mfma_f32_16x16x32_bf16 v[56:59], v[236:239], v[80:83], v[56:59]
	v_mfma_f32_16x16x32_bf16 v[60:63], v[236:239], v[88:91], v[60:63]
	s_branch .La16_fin
.La16_tail01:
	s_add_i32 s17, s14, 3
	s_min_u32 s17, s17, s15
	s_mul_i32 s18, s17, 0x30000
	s_lshl_b32 s19, s17, 7
	s_or_b32 s12, s18, 0x80
	s_add_i32 s13, s19, 0x200000
	s_add_i32 s17, s14, 0
	s_lshl_b32 s17, s17, 6
	v_subrev_u32_e32 v248, s17, v246
	v_subrev_u32_e32 v249, s17, v247
	v_cmp_gt_i32_e64 vcc, 0, v248
	v_cmp_gt_i32_e64 s[98:99], 1, v248
	v_cmp_gt_i32_e64 s[100:101], 2, v248
	v_cndmask_b32_e64 v96, v96, v197, vcc
	v_cmp_gt_i32_e64 vcc, 3, v248
	v_cndmask_b32_e64 v97, v97, v197, s[98:99]
	v_cmp_gt_i32_e64 s[98:99], 8, v248
	v_cndmask_b32_e64 v98, v98, v197, s[100:101]
	v_cmp_gt_i32_e64 s[100:101], 9, v248
	v_cndmask_b32_e64 v99, v99, v197, vcc
	v_cmp_gt_i32_e64 vcc, 10, v248
	v_cndmask_b32_e64 v100, v100, v197, s[98:99]
	v_cmp_gt_i32_e64 s[98:99], 11, v248
	v_cndmask_b32_e64 v101, v101, v197, s[100:101]
	v_cmp_gt_i32_e64 s[100:101], 0, v249
	v_cndmask_b32_e64 v102, v102, v197, vcc
	v_cmp_gt_i32_e64 vcc, 1, v249
	v_cndmask_b32_e64 v103, v103, v197, s[98:99]
	v_cmp_gt_i32_e64 s[98:99], 2, v249
	v_cndmask_b32_e64 v104, v104, v197, s[100:101]
	v_cmp_gt_i32_e64 s[100:101], 3, v249
	v_cndmask_b32_e64 v105, v105, v197, vcc
	v_cmp_gt_i32_e64 vcc, 8, v249
	v_cndmask_b32_e64 v106, v106, v197, s[98:99]
	v_cmp_gt_i32_e64 s[98:99], 9, v249
	v_cndmask_b32_e64 v107, v107, v197, s[100:101]
	v_cmp_gt_i32_e64 s[100:101], 10, v249
	v_cndmask_b32_e64 v108, v108, v197, vcc
	v_cmp_gt_i32_e64 vcc, 11, v249
	v_cndmask_b32_e64 v109, v109, v197, s[98:99]
	v_cmp_gt_i32_e64 s[98:99], 32, v248
	v_cndmask_b32_e64 v110, v110, v197, s[100:101]
	v_cmp_gt_i32_e64 s[100:101], 33, v248
	v_cndmask_b32_e64 v111, v111, v197, vcc
	v_cmp_gt_i32_e64 vcc, 34, v248
	v_cndmask_b32_e64 v112, v112, v197, s[98:99]
	v_cmp_gt_i32_e64 s[98:99], 35, v248
	v_cndmask_b32_e64 v113, v113, v197, s[100:101]
	v_cmp_gt_i32_e64 s[100:101], 40, v248
	v_cndmask_b32_e64 v114, v114, v197, vcc
	v_cmp_gt_i32_e64 vcc, 41, v248
	v_cndmask_b32_e64 v115, v115, v197, s[98:99]
	v_cmp_gt_i32_e64 s[98:99], 42, v248
	v_cndmask_b32_e64 v116, v116, v197, s[100:101]
	v_cmp_gt_i32_e64 s[100:101], 43, v248
	v_cndmask_b32_e64 v117, v117, v197, vcc
	v_cmp_gt_i32_e64 vcc, 32, v249
	v_cndmask_b32_e64 v118, v118, v197, s[98:99]
	v_cmp_gt_i32_e64 s[98:99], 33, v249
	v_cndmask_b32_e64 v119, v119, v197, s[100:101]
	v_cmp_gt_i32_e64 s[100:101], 34, v249
	v_cndmask_b32_e64 v120, v120, v197, vcc
	v_cmp_gt_i32_e64 vcc, 35, v249
	v_cndmask_b32_e64 v121, v121, v197, s[98:99]
	v_cmp_gt_i32_e64 s[98:99], 40, v249
	v_cndmask_b32_e64 v122, v122, v197, s[100:101]
	v_cmp_gt_i32_e64 s[100:101], 41, v249
	v_cndmask_b32_e64 v123, v123, v197, vcc
	v_cmp_gt_i32_e64 vcc, 42, v249
	v_cndmask_b32_e64 v124, v124, v197, s[98:99]
	v_cmp_gt_i32_e64 s[98:99], 43, v249
	v_cndmask_b32_e64 v125, v125, v197, s[100:101]
	s_nop 0
	v_cndmask_b32_e64 v126, v126, v197, vcc
	s_nop 0
	v_cndmask_b32_e64 v127, v127, v197, s[98:99]
	s_nop 0
	ds_read_b128 v[224:227], v241 offset:32768
	ds_read_b128 v[228:231], v241 offset:33792
	ds_read_b128 v[232:235], v241 offset:36864
	ds_read_b128 v[236:239], v241 offset:37888
	s_waitcnt lgkmcnt(4)
	v_mfma_f32_16x16x32_bf16 v[64:67], v[144:147], v[128:131], 0
	v_exp_f32_e32 v96, v96
	v_exp_f32_e32 v97, v97
	v_add_f32_e32 v220, v220, v96
	v_add_f32_e32 v220, v220, v97
	v_cvt_pk_bf16_f32 v96, v96, v97
	v_mfma_f32_16x16x32_bf16 v[72:75], v[144:147], v[136:139], 0
	v_exp_f32_e32 v98, v98
	v_exp_f32_e32 v99, v99
	v_add_f32_e32 v220, v220, v98
	v_add_f32_e32 v220, v220, v99
	v_cvt_pk_bf16_f32 v97, v98, v99
	v_mfma_f32_16x16x32_bf16 v[68:71], v[148:151], v[128:131], 0
	v_exp_f32_e32 v100, v100
	v_exp_f32_e32 v101, v101
	v_add_f32_e32 v220, v220, v100
	v_cvt_pk_bf16_f32 v98, v100, v101
	v_add_f32_e32 v220, v220, v101
	v_mfma_f32_16x16x32_bf16 v[76:79], v[148:151], v[136:139], 0
	v_exp_f32_e32 v102, v102
	v_exp_f32_e32 v103, v103
	v_add_f32_e32 v220, v220, v102
	v_cvt_pk_bf16_f32 v99, v102, v103
	v_add_f32_e32 v220, v220, v103
	v_mfma_f32_16x16x32_bf16 v[80:83], v[152:155], v[128:131], 0
	v_exp_f32_e32 v104, v104
	v_exp_f32_e32 v105, v105
	v_add_f32_e32 v221, v221, v104
	v_add_f32_e32 v221, v221, v105
	v_cvt_pk_bf16_f32 v104, v104, v105
	v_mfma_f32_16x16x32_bf16 v[88:91], v[152:155], v[136:139], 0
	v_exp_f32_e32 v106, v106
	v_exp_f32_e32 v107, v107
	v_add_f32_e32 v221, v221, v106
	v_add_f32_e32 v221, v221, v107
	v_cvt_pk_bf16_f32 v105, v106, v107
	v_mfma_f32_16x16x32_bf16 v[84:87], v[156:159], v[128:131], 0
	v_exp_f32_e32 v108, v108
	v_exp_f32_e32 v109, v109
	v_add_f32_e32 v221, v221, v108
	v_cvt_pk_bf16_f32 v106, v108, v109
	v_add_f32_e32 v221, v221, v109
	v_mfma_f32_16x16x32_bf16 v[92:95], v[156:159], v[136:139], 0
	v_exp_f32_e32 v110, v110
	v_exp_f32_e32 v111, v111
	v_add_f32_e32 v221, v221, v110
	v_cvt_pk_bf16_f32 v107, v110, v111
	v_add_f32_e32 v221, v221, v111
	ds_read_b128 v[144:147], v242
	ds_read_b128 v[148:151], v242 offset:2048
	ds_read_b128 v[152:155], v242 offset:4096
	ds_read_b128 v[156:159], v242 offset:6144
	s_waitcnt lgkmcnt(4)
	v_mfma_f32_16x16x32_bf16 v[64:67], v[224:227], v[132:135], v[64:67]
	v_exp_f32_e32 v112, v112
	v_exp_f32_e32 v113, v113
	v_add_f32_e32 v220, v220, v112
	v_add_f32_e32 v220, v220, v113
	v_cvt_pk_bf16_f32 v112, v112, v113
	v_mfma_f32_16x16x32_bf16 v[72:75], v[224:227], v[140:143], v[72:75]
	v_exp_f32_e32 v114, v114
	v_exp_f32_e32 v115, v115
	v_add_f32_e32 v220, v220, v114
	v_add_f32_e32 v220, v220, v115
	v_cvt_pk_bf16_f32 v113, v114, v115
	v_mfma_f32_16x16x32_bf16 v[68:71], v[228:231], v[132:135], v[68:71]
	v_exp_f32_e32 v116, v116
	v_exp_f32_e32 v117, v117
	v_add_f32_e32 v220, v220, v116
	v_cvt_pk_bf16_f32 v114, v116, v117
	v_add_f32_e32 v220, v220, v117
	v_mfma_f32_16x16x32_bf16 v[76:79], v[228:231], v[140:143], v[76:79]
	v_exp_f32_e32 v118, v118
	v_exp_f32_e32 v119, v119
	v_add_f32_e32 v220, v220, v118
	v_cvt_pk_bf16_f32 v115, v118, v119
	v_add_f32_e32 v220, v220, v119
	v_mfma_f32_16x16x32_bf16 v[80:83], v[232:235], v[132:135], v[80:83]
	v_exp_f32_e32 v120, v120
	v_exp_f32_e32 v121, v121
	v_add_f32_e32 v221, v221, v120
	v_add_f32_e32 v221, v221, v121
	v_cvt_pk_bf16_f32 v120, v120, v121
	v_mfma_f32_16x16x32_bf16 v[88:91], v[232:235], v[140:143], v[88:91]
	v_exp_f32_e32 v122, v122
	v_exp_f32_e32 v123, v123
	v_add_f32_e32 v221, v221, v122
	v_add_f32_e32 v221, v221, v123
	v_cvt_pk_bf16_f32 v121, v122, v123
	v_mfma_f32_16x16x32_bf16 v[84:87], v[236:239], v[132:135], v[84:87]
	v_exp_f32_e32 v124, v124
	v_exp_f32_e32 v125, v125
	v_add_f32_e32 v221, v221, v124
	v_cvt_pk_bf16_f32 v122, v124, v125
	v_add_f32_e32 v221, v221, v125
	v_mfma_f32_16x16x32_bf16 v[92:95], v[236:239], v[140:143], v[92:95]
	v_exp_f32_e32 v126, v126
	v_exp_f32_e32 v127, v127
	v_add_f32_e32 v221, v221, v126
	v_cvt_pk_bf16_f32 v123, v126, v127
	v_add_f32_e32 v221, v221, v127
	ds_read_b128 v[224:227], v242 offset:8192
	ds_read_b128 v[228:231], v242 offset:10240
	ds_read_b128 v[232:235], v242 offset:12288
	ds_read_b128 v[236:239], v242 offset:14336
	s_waitcnt lgkmcnt(4)
	v_mfma_f32_16x16x32_bf16 v[0:3], v[144:147], v[96:99], v[0:3]
	v_mfma_f32_16x16x32_bf16 v[4:7], v[144:147], v[104:107], v[4:7]
	v_mfma_f32_16x16x32_bf16 v[8:11], v[148:151], v[96:99], v[8:11]
	v_mfma_f32_16x16x32_bf16 v[12:15], v[148:151], v[104:107], v[12:15]
	v_mfma_f32_16x16x32_bf16 v[16:19], v[152:155], v[96:99], v[16:19]
	v_mfma_f32_16x16x32_bf16 v[20:23], v[152:155], v[104:107], v[20:23]
	v_mfma_f32_16x16x32_bf16 v[24:27], v[156:159], v[96:99], v[24:27]
	v_mfma_f32_16x16x32_bf16 v[28:31], v[156:159], v[104:107], v[28:31]
	ds_read_b128 v[144:147], v243
	ds_read_b128 v[148:151], v243 offset:2048
	ds_read_b128 v[152:155], v243 offset:4096
	ds_read_b128 v[156:159], v243 offset:6144
	s_waitcnt lgkmcnt(4)
	v_mfma_f32_16x16x32_bf16 v[32:35], v[224:227], v[96:99], v[32:35]
	v_mfma_f32_16x16x32_bf16 v[36:39], v[224:227], v[104:107], v[36:39]
	v_mfma_f32_16x16x32_bf16 v[40:43], v[228:231], v[96:99], v[40:43]
	v_mfma_f32_16x16x32_bf16 v[44:47], v[228:231], v[104:107], v[44:47]
	v_mfma_f32_16x16x32_bf16 v[48:51], v[232:235], v[96:99], v[48:51]
	v_mfma_f32_16x16x32_bf16 v[52:55], v[232:235], v[104:107], v[52:55]
	v_mfma_f32_16x16x32_bf16 v[56:59], v[236:239], v[96:99], v[56:59]
	v_mfma_f32_16x16x32_bf16 v[60:63], v[236:239], v[104:107], v[60:63]
	ds_read_b128 v[224:227], v243 offset:8192
	ds_read_b128 v[228:231], v243 offset:10240
	ds_read_b128 v[232:235], v243 offset:12288
	ds_read_b128 v[236:239], v243 offset:14336
	s_waitcnt lgkmcnt(4)
	s_mov_b32 m0, s92
	v_mfma_f32_16x16x32_bf16 v[0:3], v[144:147], v[112:115], v[0:3]
	buffer_load_dwordx4 v205, s[28:31], s18 offen lds
	s_mov_b32 m0, s93
	v_mfma_f32_16x16x32_bf16 v[4:7], v[144:147], v[120:123], v[4:7]
	buffer_load_dwordx4 v205, s[28:31], s12 offen lds
	s_mov_b32 m0, s94
	v_mfma_f32_16x16x32_bf16 v[8:11], v[148:151], v[112:115], v[8:11]
	buffer_load_dwordx4 v206, s[36:39], s19 offen lds
	s_mov_b32 m0, s95
	v_mfma_f32_16x16x32_bf16 v[12:15], v[148:151], v[120:123], v[12:15]
	buffer_load_dwordx4 v206, s[36:39], s13 offen lds
	v_mfma_f32_16x16x32_bf16 v[16:19], v[152:155], v[112:115], v[16:19]
	v_mfma_f32_16x16x32_bf16 v[20:23], v[152:155], v[120:123], v[20:23]
	v_mfma_f32_16x16x32_bf16 v[24:27], v[156:159], v[112:115], v[24:27]
	v_mfma_f32_16x16x32_bf16 v[28:31], v[156:159], v[120:123], v[28:31]
	s_waitcnt vmcnt(4) lgkmcnt(0)
	s_barrier
	ds_read_b128 v[144:147], v217
	ds_read_b128 v[148:151], v217 offset:1024
	ds_read_b128 v[152:155], v217 offset:4096
	ds_read_b128 v[156:159], v217 offset:5120
	v_mfma_f32_16x16x32_bf16 v[32:35], v[224:227], v[112:115], v[32:35]
	v_mfma_f32_16x16x32_bf16 v[36:39], v[224:227], v[120:123], v[36:39]
	v_mfma_f32_16x16x32_bf16 v[40:43], v[228:231], v[112:115], v[40:43]
	v_mfma_f32_16x16x32_bf16 v[44:47], v[228:231], v[120:123], v[44:47]
	v_mfma_f32_16x16x32_bf16 v[48:51], v[232:235], v[112:115], v[48:51]
	v_mfma_f32_16x16x32_bf16 v[52:55], v[232:235], v[120:123], v[52:55]
	v_mfma_f32_16x16x32_bf16 v[56:59], v[236:239], v[112:115], v[56:59]
	v_mfma_f32_16x16x32_bf16 v[60:63], v[236:239], v[120:123], v[60:63]
	s_add_i32 s17, s14, 4
	s_min_u32 s17, s17, s15
	s_mul_i32 s18, s17, 0x30000
	s_lshl_b32 s19, s17, 7
	s_or_b32 s12, s18, 0x80
	s_add_i32 s13, s19, 0x200000
	s_add_i32 s17, s14, 1
	s_lshl_b32 s17, s17, 6
	v_subrev_u32_e32 v248, s17, v246
	v_subrev_u32_e32 v249, s17, v247
	v_cmp_gt_i32_e64 vcc, 0, v248
	v_cmp_gt_i32_e64 s[98:99], 1, v248
	v_cmp_gt_i32_e64 s[100:101], 2, v248
	v_cndmask_b32_e64 v64, v64, v197, vcc
	v_cmp_gt_i32_e64 vcc, 3, v248
	v_cndmask_b32_e64 v65, v65, v197, s[98:99]
	v_cmp_gt_i32_e64 s[98:99], 8, v248
	v_cndmask_b32_e64 v66, v66, v197, s[100:101]
	v_cmp_gt_i32_e64 s[100:101], 9, v248
	v_cndmask_b32_e64 v67, v67, v197, vcc
	v_cmp_gt_i32_e64 vcc, 10, v248
	v_cndmask_b32_e64 v68, v68, v197, s[98:99]
	v_cmp_gt_i32_e64 s[98:99], 11, v248
	v_cndmask_b32_e64 v69, v69, v197, s[100:101]
	v_cmp_gt_i32_e64 s[100:101], 0, v249
	v_cndmask_b32_e64 v70, v70, v197, vcc
	v_cmp_gt_i32_e64 vcc, 1, v249
	v_cndmask_b32_e64 v71, v71, v197, s[98:99]
	v_cmp_gt_i32_e64 s[98:99], 2, v249
	v_cndmask_b32_e64 v72, v72, v197, s[100:101]
	v_cmp_gt_i32_e64 s[100:101], 3, v249
	v_cndmask_b32_e64 v73, v73, v197, vcc
	v_cmp_gt_i32_e64 vcc, 8, v249
	v_cndmask_b32_e64 v74, v74, v197, s[98:99]
	v_cmp_gt_i32_e64 s[98:99], 9, v249
	v_cndmask_b32_e64 v75, v75, v197, s[100:101]
	v_cmp_gt_i32_e64 s[100:101], 10, v249
	v_cndmask_b32_e64 v76, v76, v197, vcc
	v_cmp_gt_i32_e64 vcc, 11, v249
	v_cndmask_b32_e64 v77, v77, v197, s[98:99]
	v_cmp_gt_i32_e64 s[98:99], 32, v248
	v_cndmask_b32_e64 v78, v78, v197, s[100:101]
	v_cmp_gt_i32_e64 s[100:101], 33, v248
	v_cndmask_b32_e64 v79, v79, v197, vcc
	v_cmp_gt_i32_e64 vcc, 34, v248
	v_cndmask_b32_e64 v80, v80, v197, s[98:99]
	v_cmp_gt_i32_e64 s[98:99], 35, v248
	v_cndmask_b32_e64 v81, v81, v197, s[100:101]
	v_cmp_gt_i32_e64 s[100:101], 40, v248
	v_cndmask_b32_e64 v82, v82, v197, vcc
	v_cmp_gt_i32_e64 vcc, 41, v248
	v_cndmask_b32_e64 v83, v83, v197, s[98:99]
	v_cmp_gt_i32_e64 s[98:99], 42, v248
	v_cndmask_b32_e64 v84, v84, v197, s[100:101]
	v_cmp_gt_i32_e64 s[100:101], 43, v248
	v_cndmask_b32_e64 v85, v85, v197, vcc
	v_cmp_gt_i32_e64 vcc, 32, v249
	v_cndmask_b32_e64 v86, v86, v197, s[98:99]
	v_cmp_gt_i32_e64 s[98:99], 33, v249
	v_cndmask_b32_e64 v87, v87, v197, s[100:101]
	v_cmp_gt_i32_e64 s[100:101], 34, v249
	v_cndmask_b32_e64 v88, v88, v197, vcc
	v_cmp_gt_i32_e64 vcc, 35, v249
	v_cndmask_b32_e64 v89, v89, v197, s[98:99]
	v_cmp_gt_i32_e64 s[98:99], 40, v249
	v_cndmask_b32_e64 v90, v90, v197, s[100:101]
	v_cmp_gt_i32_e64 s[100:101], 41, v249
	v_cndmask_b32_e64 v91, v91, v197, vcc
	v_cmp_gt_i32_e64 vcc, 42, v249
	v_cndmask_b32_e64 v92, v92, v197, s[98:99]
	v_cmp_gt_i32_e64 s[98:99], 43, v249
	v_cndmask_b32_e64 v93, v93, v197, s[100:101]
	s_nop 0
	v_cndmask_b32_e64 v94, v94, v197, vcc
	s_nop 0
	v_cndmask_b32_e64 v95, v95, v197, s[98:99]
	s_nop 0
	ds_read_b128 v[224:227], v218
	ds_read_b128 v[228:231], v218 offset:1024
	ds_read_b128 v[232:235], v218 offset:4096
	ds_read_b128 v[236:239], v218 offset:5120
	s_waitcnt lgkmcnt(4)
	v_mfma_f32_16x16x32_bf16 v[96:99], v[144:147], v[128:131], 0
	v_exp_f32_e32 v64, v64
	v_exp_f32_e32 v65, v65
	v_add_f32_e32 v220, v220, v64
	v_add_f32_e32 v220, v220, v65
	v_cvt_pk_bf16_f32 v64, v64, v65
	v_mfma_f32_16x16x32_bf16 v[104:107], v[144:147], v[136:139], 0
	v_exp_f32_e32 v66, v66
	v_exp_f32_e32 v67, v67
	v_add_f32_e32 v220, v220, v66
	v_add_f32_e32 v220, v220, v67
	v_cvt_pk_bf16_f32 v65, v66, v67
	v_mfma_f32_16x16x32_bf16 v[100:103], v[148:151], v[128:131], 0
	v_exp_f32_e32 v68, v68
	v_exp_f32_e32 v69, v69
	v_add_f32_e32 v220, v220, v68
	v_cvt_pk_bf16_f32 v66, v68, v69
	v_add_f32_e32 v220, v220, v69
	v_mfma_f32_16x16x32_bf16 v[108:111], v[148:151], v[136:139], 0
	v_exp_f32_e32 v70, v70
	v_exp_f32_e32 v71, v71
	v_add_f32_e32 v220, v220, v70
	v_cvt_pk_bf16_f32 v67, v70, v71
	v_add_f32_e32 v220, v220, v71
	v_mfma_f32_16x16x32_bf16 v[112:115], v[152:155], v[128:131], 0
	v_exp_f32_e32 v72, v72
	v_exp_f32_e32 v73, v73
	v_add_f32_e32 v221, v221, v72
	v_add_f32_e32 v221, v221, v73
	v_cvt_pk_bf16_f32 v72, v72, v73
	v_mfma_f32_16x16x32_bf16 v[120:123], v[152:155], v[136:139], 0
	v_exp_f32_e32 v74, v74
	v_exp_f32_e32 v75, v75
	v_add_f32_e32 v221, v221, v74
	v_add_f32_e32 v221, v221, v75
	v_cvt_pk_bf16_f32 v73, v74, v75
	v_mfma_f32_16x16x32_bf16 v[116:119], v[156:159], v[128:131], 0
	v_exp_f32_e32 v76, v76
	v_exp_f32_e32 v77, v77
	v_add_f32_e32 v221, v221, v76
	v_cvt_pk_bf16_f32 v74, v76, v77
	v_add_f32_e32 v221, v221, v77
	v_mfma_f32_16x16x32_bf16 v[124:127], v[156:159], v[136:139], 0
	v_exp_f32_e32 v78, v78
	v_exp_f32_e32 v79, v79
	v_add_f32_e32 v221, v221, v78
	v_cvt_pk_bf16_f32 v75, v78, v79
	v_add_f32_e32 v221, v221, v79
	ds_read_b128 v[144:147], v242 offset:32768
	ds_read_b128 v[148:151], v242 offset:34816
	ds_read_b128 v[152:155], v242 offset:36864
	ds_read_b128 v[156:159], v242 offset:38912
	s_waitcnt lgkmcnt(4)
	v_mfma_f32_16x16x32_bf16 v[96:99], v[224:227], v[132:135], v[96:99]
	v_exp_f32_e32 v80, v80
	v_exp_f32_e32 v81, v81
	v_add_f32_e32 v220, v220, v80
	v_add_f32_e32 v220, v220, v81
	v_cvt_pk_bf16_f32 v80, v80, v81
	v_mfma_f32_16x16x32_bf16 v[104:107], v[224:227], v[140:143], v[104:107]
	v_exp_f32_e32 v82, v82
	v_exp_f32_e32 v83, v83
	v_add_f32_e32 v220, v220, v82
	v_add_f32_e32 v220, v220, v83
	v_cvt_pk_bf16_f32 v81, v82, v83
	v_mfma_f32_16x16x32_bf16 v[100:103], v[228:231], v[132:135], v[100:103]
	v_exp_f32_e32 v84, v84
	v_exp_f32_e32 v85, v85
	v_add_f32_e32 v220, v220, v84
	v_cvt_pk_bf16_f32 v82, v84, v85
	v_add_f32_e32 v220, v220, v85
	v_mfma_f32_16x16x32_bf16 v[108:111], v[228:231], v[140:143], v[108:111]
	v_exp_f32_e32 v86, v86
	v_exp_f32_e32 v87, v87
	v_add_f32_e32 v220, v220, v86
	v_cvt_pk_bf16_f32 v83, v86, v87
	v_add_f32_e32 v220, v220, v87
	v_mfma_f32_16x16x32_bf16 v[112:115], v[232:235], v[132:135], v[112:115]
	v_exp_f32_e32 v88, v88
	v_exp_f32_e32 v89, v89
	v_add_f32_e32 v221, v221, v88
	v_add_f32_e32 v221, v221, v89
	v_cvt_pk_bf16_f32 v88, v88, v89
	v_mfma_f32_16x16x32_bf16 v[120:123], v[232:235], v[140:143], v[120:123]
	v_exp_f32_e32 v90, v90
	v_exp_f32_e32 v91, v91
	v_add_f32_e32 v221, v221, v90
	v_add_f32_e32 v221, v221, v91
	v_cvt_pk_bf16_f32 v89, v90, v91
	v_mfma_f32_16x16x32_bf16 v[116:119], v[236:239], v[132:135], v[116:119]
	v_exp_f32_e32 v92, v92
	v_exp_f32_e32 v93, v93
	v_add_f32_e32 v221, v221, v92
	v_cvt_pk_bf16_f32 v90, v92, v93
	v_add_f32_e32 v221, v221, v93
	v_mfma_f32_16x16x32_bf16 v[124:127], v[236:239], v[140:143], v[124:127]
	v_exp_f32_e32 v94, v94
	v_exp_f32_e32 v95, v95
	v_add_f32_e32 v221, v221, v94
	v_cvt_pk_bf16_f32 v91, v94, v95
	v_add_f32_e32 v221, v221, v95
	ds_read_b128 v[224:227], v242 offset:40960
	ds_read_b128 v[228:231], v242 offset:43008
	ds_read_b128 v[232:235], v242 offset:45056
	ds_read_b128 v[236:239], v242 offset:47104
	s_waitcnt lgkmcnt(4)
	v_mfma_f32_16x16x32_bf16 v[0:3], v[144:147], v[64:67], v[0:3]
	v_mfma_f32_16x16x32_bf16 v[4:7], v[144:147], v[72:75], v[4:7]
	v_mfma_f32_16x16x32_bf16 v[8:11], v[148:151], v[64:67], v[8:11]
	v_mfma_f32_16x16x32_bf16 v[12:15], v[148:151], v[72:75], v[12:15]
	v_mfma_f32_16x16x32_bf16 v[16:19], v[152:155], v[64:67], v[16:19]
	v_mfma_f32_16x16x32_bf16 v[20:23], v[152:155], v[72:75], v[20:23]
	v_mfma_f32_16x16x32_bf16 v[24:27], v[156:159], v[64:67], v[24:27]
	v_mfma_f32_16x16x32_bf16 v[28:31], v[156:159], v[72:75], v[28:31]
	ds_read_b128 v[144:147], v243 offset:32768
	ds_read_b128 v[148:151], v243 offset:34816
	ds_read_b128 v[152:155], v243 offset:36864
	ds_read_b128 v[156:159], v243 offset:38912
	s_waitcnt lgkmcnt(4)
	v_mfma_f32_16x16x32_bf16 v[32:35], v[224:227], v[64:67], v[32:35]
	v_mfma_f32_16x16x32_bf16 v[36:39], v[224:227], v[72:75], v[36:39]
	v_mfma_f32_16x16x32_bf16 v[40:43], v[228:231], v[64:67], v[40:43]
	v_mfma_f32_16x16x32_bf16 v[44:47], v[228:231], v[72:75], v[44:47]
	v_mfma_f32_16x16x32_bf16 v[48:51], v[232:235], v[64:67], v[48:51]
	v_mfma_f32_16x16x32_bf16 v[52:55], v[232:235], v[72:75], v[52:55]
	v_mfma_f32_16x16x32_bf16 v[56:59], v[236:239], v[64:67], v[56:59]
	v_mfma_f32_16x16x32_bf16 v[60:63], v[236:239], v[72:75], v[60:63]
	ds_read_b128 v[224:227], v243 offset:40960
	ds_read_b128 v[228:231], v243 offset:43008
	ds_read_b128 v[232:235], v243 offset:45056
	ds_read_b128 v[236:239], v243 offset:47104
	s_waitcnt lgkmcnt(4)
	s_mov_b32 m0, s72
	v_mfma_f32_16x16x32_bf16 v[0:3], v[144:147], v[80:83], v[0:3]
	buffer_load_dwordx4 v205, s[28:31], s18 offen lds
	s_mov_b32 m0, s73
	v_mfma_f32_16x16x32_bf16 v[4:7], v[144:147], v[88:91], v[4:7]
	buffer_load_dwordx4 v205, s[28:31], s12 offen lds
	s_mov_b32 m0, s6
	v_mfma_f32_16x16x32_bf16 v[8:11], v[148:151], v[80:83], v[8:11]
	buffer_load_dwordx4 v206, s[36:39], s19 offen lds
	s_mov_b32 m0, s7
	v_mfma_f32_16x16x32_bf16 v[12:15], v[148:151], v[88:91], v[12:15]
	buffer_load_dwordx4 v206, s[36:39], s13 offen lds
	v_mfma_f32_16x16x32_bf16 v[16:19], v[152:155], v[80:83], v[16:19]
	v_mfma_f32_16x16x32_bf16 v[20:23], v[152:155], v[88:91], v[20:23]
	v_mfma_f32_16x16x32_bf16 v[24:27], v[156:159], v[80:83], v[24:27]
	v_mfma_f32_16x16x32_bf16 v[28:31], v[156:159], v[88:91], v[28:31]
	s_waitcnt vmcnt(4) lgkmcnt(0)
	s_barrier
	ds_read_b128 v[144:147], v217 offset:32768
	ds_read_b128 v[148:151], v217 offset:33792
	ds_read_b128 v[152:155], v217 offset:36864
	ds_read_b128 v[156:159], v217 offset:37888
	v_mfma_f32_16x16x32_bf16 v[32:35], v[224:227], v[80:83], v[32:35]
	v_mfma_f32_16x16x32_bf16 v[36:39], v[224:227], v[88:91], v[36:39]
	v_mfma_f32_16x16x32_bf16 v[40:43], v[228:231], v[80:83], v[40:43]
	v_mfma_f32_16x16x32_bf16 v[44:47], v[228:231], v[88:91], v[44:47]
	v_mfma_f32_16x16x32_bf16 v[48:51], v[232:235], v[80:83], v[48:51]
	v_mfma_f32_16x16x32_bf16 v[52:55], v[232:235], v[88:91], v[52:55]
	v_mfma_f32_16x16x32_bf16 v[56:59], v[236:239], v[80:83], v[56:59]
	v_mfma_f32_16x16x32_bf16 v[60:63], v[236:239], v[88:91], v[60:63]
.La16_fin:
	s_waitcnt vmcnt(0) lgkmcnt(0)
	s_barrier
	ds_bpermute_b32 v252, v180, v220
	s_waitcnt lgkmcnt(0)
	v_add_f32_e32 v220, v220, v252
	ds_bpermute_b32 v252, v181, v220
	s_waitcnt lgkmcnt(0)
	v_add_f32_e32 v220, v220, v252
	ds_bpermute_b32 v252, v180, v221
	s_waitcnt lgkmcnt(0)
	v_add_f32_e32 v221, v221, v252
	ds_bpermute_b32 v252, v181, v221
	s_waitcnt lgkmcnt(0)
	v_add_f32_e32 v221, v221, v252
	v_rcp_f32_e32 v248, v220
	v_rcp_f32_e32 v249, v221
	s_nop 0
	v_fma_f32 v252, -v220, v248, 2.0
	v_mul_f32_e32 v248, v248, v252
	v_fma_f32 v252, -v221, v249, 2.0
	v_mul_f32_e32 v249, v249, v252
	v_add_u32_e32 v252, s68, v250
	v_lshlrev_b32_e32 v252, 9, v252
	v_lshl_add_u32 v252, v251, 4, v252
	s_lshl_b32 s17, s69, 10
	s_add_i32 s17, s17, 0x120
	v_add_u32_e32 v252, s17, v252
	v_mul_f32_e32 v0, v0, v248
	v_mul_f32_e32 v1, v1, v248
	v_mul_f32_e32 v2, v2, v248
	v_mul_f32_e32 v3, v3, v248
	ds_write_b128 v252, v[0:3]
	v_mul_f32_e32 v8, v8, v248
	v_mul_f32_e32 v9, v9, v248
	v_mul_f32_e32 v10, v10, v248
	v_mul_f32_e32 v11, v11, v248
	ds_write_b128 v252, v[8:11] offset:64
	v_mul_f32_e32 v16, v16, v248
	v_mul_f32_e32 v17, v17, v248
	v_mul_f32_e32 v18, v18, v248
	v_mul_f32_e32 v19, v19, v248
	ds_write_b128 v252, v[16:19] offset:128
	v_mul_f32_e32 v24, v24, v248
	v_mul_f32_e32 v25, v25, v248
	v_mul_f32_e32 v26, v26, v248
	v_mul_f32_e32 v27, v27, v248
	ds_write_b128 v252, v[24:27] offset:192
	v_mul_f32_e32 v32, v32, v248
	v_mul_f32_e32 v33, v33, v248
	v_mul_f32_e32 v34, v34, v248
	v_mul_f32_e32 v35, v35, v248
	ds_write_b128 v252, v[32:35] offset:256
	v_mul_f32_e32 v40, v40, v248
	v_mul_f32_e32 v41, v41, v248
	v_mul_f32_e32 v42, v42, v248
	v_mul_f32_e32 v43, v43, v248
	ds_write_b128 v252, v[40:43] offset:320
	v_mul_f32_e32 v48, v48, v248
	v_mul_f32_e32 v49, v49, v248
	v_mul_f32_e32 v50, v50, v248
	v_mul_f32_e32 v51, v51, v248
	ds_write_b128 v252, v[48:51] offset:384
	v_mul_f32_e32 v56, v56, v248
	v_mul_f32_e32 v57, v57, v248
	v_mul_f32_e32 v58, v58, v248
	v_mul_f32_e32 v59, v59, v248
	ds_write_b128 v252, v[56:59] offset:448
	v_mul_f32_e32 v4, v4, v249
	v_mul_f32_e32 v5, v5, v249
	v_mul_f32_e32 v6, v6, v249
	v_mul_f32_e32 v7, v7, v249
	ds_write_b128 v252, v[4:7] offset:8192
	v_mul_f32_e32 v12, v12, v249
	v_mul_f32_e32 v13, v13, v249
	v_mul_f32_e32 v14, v14, v249
	v_mul_f32_e32 v15, v15, v249
	ds_write_b128 v252, v[12:15] offset:8256
	v_mul_f32_e32 v20, v20, v249
	v_mul_f32_e32 v21, v21, v249
	v_mul_f32_e32 v22, v22, v249
	v_mul_f32_e32 v23, v23, v249
	ds_write_b128 v252, v[20:23] offset:8320
	v_mul_f32_e32 v28, v28, v249
	v_mul_f32_e32 v29, v29, v249
	v_mul_f32_e32 v30, v30, v249
	v_mul_f32_e32 v31, v31, v249
	ds_write_b128 v252, v[28:31] offset:8384
	v_mul_f32_e32 v36, v36, v249
	v_mul_f32_e32 v37, v37, v249
	v_mul_f32_e32 v38, v38, v249
	v_mul_f32_e32 v39, v39, v249
	ds_write_b128 v252, v[36:39] offset:8448
	v_mul_f32_e32 v44, v44, v249
	v_mul_f32_e32 v45, v45, v249
	v_mul_f32_e32 v46, v46, v249
	v_mul_f32_e32 v47, v47, v249
	ds_write_b128 v252, v[44:47] offset:8512
	v_mul_f32_e32 v52, v52, v249
	v_mul_f32_e32 v53, v53, v249
	v_mul_f32_e32 v54, v54, v249
	v_mul_f32_e32 v55, v55, v249
	ds_write_b128 v252, v[52:55] offset:8576
	v_mul_f32_e32 v60, v60, v249
	v_mul_f32_e32 v61, v61, v249
	v_mul_f32_e32 v62, v62, v249
	v_mul_f32_e32 v63, v63, v249
	ds_write_b128 v252, v[60:63] offset:8640
	s_waitcnt lgkmcnt(0)
	s_barrier
	v_lshlrev_b32_e32 v128, 9, v213
	v_lshl_add_u32 v128, v160, 1, v128
	v_add_u32_e32 v128, 0x120, v128
	v_add_u32_e32 v129, 0x10000, v128
	ds_read_b128 v[0:3], v128
	ds_read_b128 v[4:7], v128 offset:16
	ds_read_b128 v[8:11], v128 offset:32
	ds_read_b128 v[12:15], v128 offset:48
	ds_read_b128 v[16:19], v128 offset:64
	ds_read_b128 v[20:23], v128 offset:80
	ds_read_b128 v[24:27], v128 offset:96
	ds_read_b128 v[28:31], v128 offset:112
	ds_read_b128 v[32:35], v129
	ds_read_b128 v[36:39], v129 offset:16
	ds_read_b128 v[40:43], v129 offset:32
	ds_read_b128 v[44:47], v129 offset:48
	ds_read_b128 v[48:51], v129 offset:64
	ds_read_b128 v[52:55], v129 offset:80
	ds_read_b128 v[56:59], v129 offset:96
	ds_read_b128 v[60:63], v129 offset:112
	v_lshlrev_b32_e32 v130, 1, v160
	global_load_dwordx4 v[64:67], v130, s[56:57]
	global_load_dwordx4 v[68:71], v130, s[56:57] offset:16
	global_load_dwordx4 v[72:75], v130, s[56:57] offset:32
	global_load_dwordx4 v[76:79], v130, s[56:57] offset:48
	global_load_dwordx4 v[80:83], v130, s[56:57] offset:64
	global_load_dwordx4 v[84:87], v130, s[56:57] offset:80
	global_load_dwordx4 v[88:91], v130, s[56:57] offset:96
	global_load_dwordx4 v[92:95], v130, s[56:57] offset:112
	v_add_u32_e32 v132, s40, v213
	v_ashrrev_i32_e32 v133, 31, v132
	v_lshlrev_b64 v[132:133], 11, v[132:133]
	v_lshl_add_u64 v[132:133], s[42:43], 0, v[132:133]
	s_lshl_b32 s40, s97, 1
	v_lshl_add_u64 v[132:133], v[132:133], 0, s[40:41]
	v_lshl_add_u64 v[132:133], v[132:133], 0, v[160:161]
	s_mov_b64 s[18:19], 0x5000400
	v_lshl_add_u64 v[132:133], v[132:133], 0, s[18:19]
	s_waitcnt lgkmcnt(0)
	v_mov_b32_e32 v131, 0
	v_fma_f32 v0, -v170, v32, v0
	v_fma_f32 v1, -v170, v33, v1
	v_fma_f32 v2, -v170, v34, v2
	v_fma_f32 v3, -v170, v35, v3
	v_fma_f32 v4, -v170, v36, v4
	v_fma_f32 v5, -v170, v37, v5
	v_fma_f32 v6, -v170, v38, v6
	v_fma_f32 v7, -v170, v39, v7
	v_fma_f32 v8, -v170, v40, v8
	v_fma_f32 v9, -v170, v41, v9
	v_fma_f32 v10, -v170, v42, v10
	v_fma_f32 v11, -v170, v43, v11
	v_fma_f32 v12, -v170, v44, v12
	v_fma_f32 v13, -v170, v45, v13
	v_fma_f32 v14, -v170, v46, v14
	v_fma_f32 v15, -v170, v47, v15
	v_fma_f32 v16, -v170, v48, v16
	v_fma_f32 v17, -v170, v49, v17
	v_fma_f32 v18, -v170, v50, v18
	v_fma_f32 v19, -v170, v51, v19
	v_fma_f32 v20, -v170, v52, v20
	v_fma_f32 v21, -v170, v53, v21
	v_fma_f32 v22, -v170, v54, v22
	v_fma_f32 v23, -v170, v55, v23
	v_fma_f32 v24, -v170, v56, v24
	v_fma_f32 v25, -v170, v57, v25
	v_fma_f32 v26, -v170, v58, v26
	v_fma_f32 v27, -v170, v59, v27
	v_fma_f32 v28, -v170, v60, v28
	v_fma_f32 v29, -v170, v61, v29
	v_fma_f32 v30, -v170, v62, v30
	v_fma_f32 v31, -v170, v63, v31
	v_fmac_f32_e32 v131, v0, v0
	v_fmac_f32_e32 v131, v1, v1
	v_fmac_f32_e32 v131, v2, v2
	v_fmac_f32_e32 v131, v3, v3
	v_fmac_f32_e32 v131, v4, v4
	v_fmac_f32_e32 v131, v5, v5
	v_fmac_f32_e32 v131, v6, v6
	v_fmac_f32_e32 v131, v7, v7
	v_fmac_f32_e32 v131, v8, v8
	v_fmac_f32_e32 v131, v9, v9
	v_fmac_f32_e32 v131, v10, v10
	v_fmac_f32_e32 v131, v11, v11
	v_fmac_f32_e32 v131, v12, v12
	v_fmac_f32_e32 v131, v13, v13
	v_fmac_f32_e32 v131, v14, v14
	v_fmac_f32_e32 v131, v15, v15
	v_fmac_f32_e32 v131, v16, v16
	v_fmac_f32_e32 v131, v17, v17
	v_fmac_f32_e32 v131, v18, v18
	v_fmac_f32_e32 v131, v19, v19
	v_fmac_f32_e32 v131, v20, v20
	v_fmac_f32_e32 v131, v21, v21
	v_fmac_f32_e32 v131, v22, v22
	v_fmac_f32_e32 v131, v23, v23
	v_fmac_f32_e32 v131, v24, v24
	v_fmac_f32_e32 v131, v25, v25
	v_fmac_f32_e32 v131, v26, v26
	v_fmac_f32_e32 v131, v27, v27
	v_fmac_f32_e32 v131, v28, v28
	v_fmac_f32_e32 v131, v29, v29
	v_fmac_f32_e32 v131, v30, v30
	v_fmac_f32_e32 v131, v31, v31
	s_nop 1
	v_add_f32_dpp v131, v131, v131 quad_perm:[1,0,3,2] row_mask:0xf bank_mask:0xf bound_ctrl:1
	s_nop 1
	v_add_f32_dpp v131, v131, v131 quad_perm:[2,3,0,1] row_mask:0xf bank_mask:0xf bound_ctrl:1
	v_mov_b32_e32 v134, 0x358637bd
	v_fmac_f32_e32 v134, 0x3c000000, v131
	v_rsq_f32_e32 v135, v134
	s_nop 0
	v_mul_f32_e32 v136, v134, v135
	v_mul_f32_e32 v136, v136, v135
	v_mov_b32_e32 v137, 0x3fc00000
	v_fma_f32 v136, v136, -0.5, v137
	v_mul_f32_e32 v135, v135, v136
	v_mul_f32_e32 v135, v135, v200
	s_waitcnt vmcnt(0)
	v_mul_f32_e32 v0, v0, v135
	v_mul_f32_e32 v1, v1, v135
	v_mul_f32_e32 v2, v2, v135
	v_mul_f32_e32 v3, v3, v135
	v_mul_f32_e32 v4, v4, v135
	v_mul_f32_e32 v5, v5, v135
	v_mul_f32_e32 v6, v6, v135
	v_mul_f32_e32 v7, v7, v135
	v_mul_f32_e32 v8, v8, v135
	v_mul_f32_e32 v9, v9, v135
	v_mul_f32_e32 v10, v10, v135
	v_mul_f32_e32 v11, v11, v135
	v_mul_f32_e32 v12, v12, v135
	v_mul_f32_e32 v13, v13, v135
	v_mul_f32_e32 v14, v14, v135
	v_mul_f32_e32 v15, v15, v135
	v_mul_f32_e32 v16, v16, v135
	v_mul_f32_e32 v17, v17, v135
	v_mul_f32_e32 v18, v18, v135
	v_mul_f32_e32 v19, v19, v135
	v_mul_f32_e32 v20, v20, v135
	v_mul_f32_e32 v21, v21, v135
	v_mul_f32_e32 v22, v22, v135
	v_mul_f32_e32 v23, v23, v135
	v_mul_f32_e32 v24, v24, v135
	v_mul_f32_e32 v25, v25, v135
	v_mul_f32_e32 v26, v26, v135
	v_mul_f32_e32 v27, v27, v135
	v_mul_f32_e32 v28, v28, v135
	v_mul_f32_e32 v29, v29, v135
	v_mul_f32_e32 v30, v30, v135
	v_mul_f32_e32 v31, v31, v135
	v_mul_f32_e32 v0, v0, v64
	v_mul_f32_e32 v1, v1, v65
	v_mul_f32_e32 v2, v2, v66
	v_mul_f32_e32 v3, v3, v67
	v_mul_f32_e32 v4, v4, v68
	v_mul_f32_e32 v5, v5, v69
	v_mul_f32_e32 v6, v6, v70
	v_mul_f32_e32 v7, v7, v71
	v_mul_f32_e32 v8, v8, v72
	v_mul_f32_e32 v9, v9, v73
	v_mul_f32_e32 v10, v10, v74
	v_mul_f32_e32 v11, v11, v75
	v_mul_f32_e32 v12, v12, v76
	v_mul_f32_e32 v13, v13, v77
	v_mul_f32_e32 v14, v14, v78
	v_mul_f32_e32 v15, v15, v79
	v_mul_f32_e32 v16, v16, v80
	v_mul_f32_e32 v17, v17, v81
	v_mul_f32_e32 v18, v18, v82
	v_mul_f32_e32 v19, v19, v83
	v_mul_f32_e32 v20, v20, v84
	v_mul_f32_e32 v21, v21, v85
	v_mul_f32_e32 v22, v22, v86
	v_mul_f32_e32 v23, v23, v87
	v_mul_f32_e32 v24, v24, v88
	v_mul_f32_e32 v25, v25, v89
	v_mul_f32_e32 v26, v26, v90
	v_mul_f32_e32 v27, v27, v91
	v_mul_f32_e32 v28, v28, v92
	v_mul_f32_e32 v29, v29, v93
	v_mul_f32_e32 v30, v30, v94
	v_mul_f32_e32 v31, v31, v95
	v_cvt_pk_bf16_f32 v96, v0, v1
	v_cvt_pk_bf16_f32 v97, v2, v3
	v_cvt_pk_bf16_f32 v98, v4, v5
	v_cvt_pk_bf16_f32 v99, v6, v7
	v_cvt_pk_bf16_f32 v100, v8, v9
	v_cvt_pk_bf16_f32 v101, v10, v11
	v_cvt_pk_bf16_f32 v102, v12, v13
	v_cvt_pk_bf16_f32 v103, v14, v15
	v_cvt_pk_bf16_f32 v104, v16, v17
	v_cvt_pk_bf16_f32 v105, v18, v19
	v_cvt_pk_bf16_f32 v106, v20, v21
	v_cvt_pk_bf16_f32 v107, v22, v23
	v_cvt_pk_bf16_f32 v108, v24, v25
	v_cvt_pk_bf16_f32 v109, v26, v27
	v_cvt_pk_bf16_f32 v110, v28, v29
	v_cvt_pk_bf16_f32 v111, v30, v31
	global_store_dwordx4 v[132:133], v[96:99], off
	global_store_dwordx4 v[132:133], v[100:103], off offset:16
	global_store_dwordx4 v[132:133], v[104:107], off offset:32
	global_store_dwordx4 v[132:133], v[108:111], off offset:48
	s_barrier
	s_add_i32 s96, s96, s34
	s_cmpk_lt_i32 s96, 0x200
	s_cbranch_scc1 .LBB0_401
	s_branch .LBB0_422
